# GEMM epilogue output stores made write-through (sc1) to shrink the release-fence cost at grid barriers
# baseline (speedup 1.0000x reference)
; __device__ __forceinline__ unsigned pk2(float lo, float hi) { f32x2 v = {lo, hi}; bf16x2_t b = __builtin_convertvector(v, bf16x2_t); return __builtin_bit_cast(unsigned, b); }
; __device__ __forceinline__ float siluf_(float x) { return x * sigmoidf_(x); }
;     __device__ __forceinline__ void operator()(const f32x4 (&acc)[2][2][4][2], const Unit& u, int wr, int wc, int fr, int fq) const {
;         const int row0 = u.pm * BM + wr * 64 + fr, col0 = u.pn * 128 + wc * 32 + 8 * fq;
; #pragma unroll
;         for (int ai = 0; ai < 2; ++ai)
; #pragma unroll
;             for (int m = 0; m < 4; ++m) {
;                 bf16_t* rowp = O + (size_t)(row0 + ai * HALF + m * 16) * FF + col0;
;                 const f32x4 g0 = acc[ai][0][m][0], g1 = acc[ai][0][m][1], u0 = acc[ai][1][m][0], u1 = acc[ai][1][m][1];
;                 f32x4 h0, h1;
; #pragma unroll
;                 for (int j = 0; j < 4; ++j) { h0[j] = siluf_(g0[j]) * u0[j]; h1[j] = siluf_(g1[j]) * u1[j]; }
;                 u32x4 w; w.x = pk2(h0[0], h0[1]); w.y = pk2(h0[2], h0[3]); w.z = pk2(h1[0], h1[1]); w.w = pk2(h1[2], h1[3]);
;                 *(u32x4*)rowp = w;
;             }
;     }
.LBB0_54:
	v_mul_f32_e32 v143, 0xbfb8aa3b, v126
	v_exp_f32_e32 v143, v143
	v_lshl_or_b32 v144, s61, 7, v140
	v_lshl_add_u32 v142, s60, 8, v138
	v_ashrrev_i32_e32 v145, 31, v144
	v_add_f32_e32 v143, 1.0, v143
	v_rcp_f32_e32 v166, v143
	v_mul_f32_e32 v143, 0xbfb8aa3b, v118
	v_exp_f32_e32 v143, v143
	v_mov_b64_e32 v[136:137], s[40:41]
	v_mad_i64_i32 v[164:165], s[60:61], v142, s24, v[136:137]
	v_add_f32_e32 v143, 1.0, v143
	v_rcp_f32_e32 v168, v143
	v_mul_f32_e32 v143, 0xbfb8aa3b, v127
	v_exp_f32_e32 v143, v143
	s_andn2_b64 vcc, exec, s[42:43]
	v_add_f32_e32 v143, 1.0, v143
	v_rcp_f32_e32 v167, v143
	s_nop 0
	v_pk_mul_f32 v[126:127], v[126:127], v[166:167]
	s_nop 0
	v_pk_mul_f32 v[122:123], v[126:127], v[122:123]
	v_mul_f32_e32 v126, 0xbfb8aa3b, v119
	v_exp_f32_e32 v126, v126
	s_nop 0
	v_add_f32_e32 v126, 1.0, v126
	v_rcp_f32_e32 v169, v126
	s_nop 0
	v_pk_mul_f32 v[118:119], v[118:119], v[168:169]
	s_nop 0
	v_pk_mul_f32 v[118:119], v[118:119], v[114:115]
	v_mul_f32_e32 v115, 0xbfb8aa3b, v120
	v_exp_f32_e32 v115, v115
	v_mul_f32_e32 v114, 0xbfb8aa3b, v128
	v_exp_f32_e32 v114, v114
	v_cvt_pk_bf16_f32 v118, v118, v119
	v_add_f32_e32 v115, 1.0, v115
	v_rcp_f32_e32 v126, v115
	v_mul_f32_e32 v115, 0xbfb8aa3b, v129
	v_exp_f32_e32 v115, v115
	v_add_f32_e32 v114, 1.0, v114
	v_rcp_f32_e32 v114, v114
	v_add_f32_e32 v115, 1.0, v115
	v_rcp_f32_e32 v115, v115
	s_nop 0
	v_pk_mul_f32 v[114:115], v[128:129], v[114:115]
	s_nop 0
	v_pk_mul_f32 v[124:125], v[114:115], v[124:125]
	v_mul_f32_e32 v114, 0xbfb8aa3b, v121
	v_exp_f32_e32 v114, v114
	s_nop 0
	v_add_f32_e32 v114, 1.0, v114
	v_rcp_f32_e32 v127, v114
	s_nop 0
	v_pk_mul_f32 v[114:115], v[120:121], v[126:127]
	s_nop 0
	v_pk_mul_f32 v[120:121], v[114:115], v[116:117]
	v_lshlrev_b64 v[114:115], 1, v[144:145]
	v_lshl_add_u64 v[126:127], v[164:165], 0, v[114:115]
	v_cvt_pk_bf16_f32 v116, v122, v123
	v_cvt_pk_bf16_f32 v117, v124, v125
	v_cvt_pk_bf16_f32 v119, v120, v121
	global_store_dwordx4 v[126:127], v[116:119], off sc1
	s_nop 1
	v_mul_f32_e32 v119, 0xbfb8aa3b, v102
	v_exp_f32_e32 v119, v119
	v_mul_f32_e32 v118, 0xbfb8aa3b, v110
	v_exp_f32_e32 v118, v118
	v_or_b32_e32 v116, 16, v142
	v_add_f32_e32 v119, 1.0, v119
	v_rcp_f32_e32 v120, v119
	v_mul_f32_e32 v119, 0xbfb8aa3b, v111
	v_exp_f32_e32 v119, v119
	v_add_f32_e32 v118, 1.0, v118
	v_rcp_f32_e32 v118, v118
	v_mad_i64_i32 v[116:117], s[60:61], v116, s24, v[136:137]
	v_add_f32_e32 v119, 1.0, v119
	v_rcp_f32_e32 v119, v119
	s_nop 0
	v_pk_mul_f32 v[110:111], v[110:111], v[118:119]
	s_nop 0
	v_pk_mul_f32 v[106:107], v[110:111], v[106:107]
	v_mul_f32_e32 v110, 0xbfb8aa3b, v103
	v_exp_f32_e32 v110, v110
	s_nop 0
	v_add_f32_e32 v110, 1.0, v110
	v_rcp_f32_e32 v121, v110
	s_nop 0
	v_pk_mul_f32 v[102:103], v[102:103], v[120:121]
	s_nop 0
	v_pk_mul_f32 v[102:103], v[102:103], v[98:99]
	v_mul_f32_e32 v99, 0xbfb8aa3b, v104
	v_exp_f32_e32 v99, v99
	v_mul_f32_e32 v98, 0xbfb8aa3b, v112
	v_exp_f32_e32 v98, v98
	v_add_f32_e32 v99, 1.0, v99
	v_rcp_f32_e32 v110, v99
	v_mul_f32_e32 v99, 0xbfb8aa3b, v113
	v_exp_f32_e32 v99, v99
	v_add_f32_e32 v98, 1.0, v98
	v_rcp_f32_e32 v98, v98
	v_add_f32_e32 v99, 1.0, v99
	v_rcp_f32_e32 v99, v99
	s_nop 0
	v_pk_mul_f32 v[98:99], v[112:113], v[98:99]
	s_nop 0
	v_pk_mul_f32 v[108:109], v[98:99], v[108:109]
	v_mul_f32_e32 v98, 0xbfb8aa3b, v105
	v_exp_f32_e32 v98, v98
	s_nop 0
	v_add_f32_e32 v98, 1.0, v98
	v_rcp_f32_e32 v111, v98
	s_nop 0
	v_pk_mul_f32 v[98:99], v[104:105], v[110:111]
	s_nop 0
	v_pk_mul_f32 v[104:105], v[98:99], v[100:101]
	v_lshl_add_u64 v[110:111], v[116:117], 0, v[114:115]
	v_cvt_pk_bf16_f32 v98, v106, v107
	v_cvt_pk_bf16_f32 v99, v108, v109
	v_cvt_pk_bf16_f32 v100, v102, v103
	v_cvt_pk_bf16_f32 v101, v104, v105
	global_store_dwordx4 v[110:111], v[98:101], off sc1
	s_nop 1
	v_mul_f32_e32 v101, 0xbfb8aa3b, v86
	v_exp_f32_e32 v101, v101
	v_mul_f32_e32 v100, 0xbfb8aa3b, v94
	v_exp_f32_e32 v100, v100
	v_or_b32_e32 v98, 32, v142
	v_add_f32_e32 v101, 1.0, v101
	v_rcp_f32_e32 v102, v101
	v_mul_f32_e32 v101, 0xbfb8aa3b, v95
	v_exp_f32_e32 v101, v101
	v_add_f32_e32 v100, 1.0, v100
	v_rcp_f32_e32 v100, v100
	v_mad_i64_i32 v[98:99], s[60:61], v98, s24, v[136:137]
	v_add_f32_e32 v101, 1.0, v101
	v_rcp_f32_e32 v101, v101
	s_nop 0
	v_pk_mul_f32 v[94:95], v[94:95], v[100:101]
	s_nop 0
	v_pk_mul_f32 v[90:91], v[94:95], v[90:91]
	v_mul_f32_e32 v94, 0xbfb8aa3b, v87
	v_exp_f32_e32 v94, v94
	s_nop 0
	v_add_f32_e32 v94, 1.0, v94
	v_rcp_f32_e32 v103, v94
	s_nop 0
	v_pk_mul_f32 v[86:87], v[86:87], v[102:103]
	s_nop 0
	v_pk_mul_f32 v[86:87], v[86:87], v[82:83]
	v_mul_f32_e32 v83, 0xbfb8aa3b, v88
	v_exp_f32_e32 v83, v83
	v_mul_f32_e32 v82, 0xbfb8aa3b, v96
	v_exp_f32_e32 v82, v82
	v_add_f32_e32 v83, 1.0, v83
	v_rcp_f32_e32 v94, v83
	v_mul_f32_e32 v83, 0xbfb8aa3b, v97
	v_exp_f32_e32 v83, v83
	v_add_f32_e32 v82, 1.0, v82
	v_rcp_f32_e32 v82, v82
	v_add_f32_e32 v83, 1.0, v83
	v_rcp_f32_e32 v83, v83
	s_nop 0
	v_pk_mul_f32 v[82:83], v[96:97], v[82:83]
	s_nop 0
	v_pk_mul_f32 v[92:93], v[82:83], v[92:93]
	v_mul_f32_e32 v82, 0xbfb8aa3b, v89
	v_exp_f32_e32 v82, v82
	s_nop 0
	v_add_f32_e32 v82, 1.0, v82
	v_rcp_f32_e32 v95, v82
	s_nop 0
	v_pk_mul_f32 v[82:83], v[88:89], v[94:95]
	s_nop 0
	v_pk_mul_f32 v[88:89], v[82:83], v[84:85]
	v_lshl_add_u64 v[94:95], v[98:99], 0, v[114:115]
	v_cvt_pk_bf16_f32 v82, v90, v91
	v_cvt_pk_bf16_f32 v83, v92, v93
	v_cvt_pk_bf16_f32 v84, v86, v87
	v_cvt_pk_bf16_f32 v85, v88, v89
	global_store_dwordx4 v[94:95], v[82:85], off sc1
	s_nop 1
	v_mul_f32_e32 v85, 0xbfb8aa3b, v70
	v_exp_f32_e32 v85, v85
	v_mul_f32_e32 v84, 0xbfb8aa3b, v78
	v_exp_f32_e32 v84, v84
	v_or_b32_e32 v82, 48, v142
	v_add_f32_e32 v85, 1.0, v85
	v_rcp_f32_e32 v86, v85
; __device__ __forceinline__ unsigned pk2(float lo, float hi) { f32x2 v = {lo, hi}; bf16x2_t b = __builtin_convertvector(v, bf16x2_t); return __builtin_bit_cast(unsigned, b); }
; __device__ __forceinline__ float siluf_(float x) { return x * sigmoidf_(x); }
;     __device__ __forceinline__ void operator()(const f32x4 (&acc)[2][2][4][2], const Unit& u, int wr, int wc, int fr, int fq) const {
;         const int row0 = u.pm * BM + wr * 64 + fr, col0 = u.pn * 128 + wc * 32 + 8 * fq;
; #pragma unroll
;         for (int ai = 0; ai < 2; ++ai)
; #pragma unroll
;             for (int m = 0; m < 4; ++m) {
;                 bf16_t* rowp = O + (size_t)(row0 + ai * HALF + m * 16) * FF + col0;
;                 const f32x4 g0 = acc[ai][0][m][0], g1 = acc[ai][0][m][1], u0 = acc[ai][1][m][0], u1 = acc[ai][1][m][1];
;                 f32x4 h0, h1;
; #pragma unroll
;                 for (int j = 0; j < 4; ++j) { h0[j] = siluf_(g0[j]) * u0[j]; h1[j] = siluf_(g1[j]) * u1[j]; }
;                 u32x4 w; w.x = pk2(h0[0], h0[1]); w.y = pk2(h0[2], h0[3]); w.z = pk2(h1[0], h1[1]); w.w = pk2(h1[2], h1[3]);
;                 *(u32x4*)rowp = w;
;             }
;     }
	v_mul_f32_e32 v85, 0xbfb8aa3b, v79
	v_exp_f32_e32 v85, v85
	v_add_f32_e32 v84, 1.0, v84
	v_rcp_f32_e32 v84, v84
	v_mad_i64_i32 v[82:83], s[60:61], v82, s24, v[136:137]
	v_add_f32_e32 v85, 1.0, v85
	v_rcp_f32_e32 v85, v85
	s_nop 0
	v_pk_mul_f32 v[78:79], v[78:79], v[84:85]
	s_nop 0
	v_pk_mul_f32 v[74:75], v[78:79], v[74:75]
	v_mul_f32_e32 v78, 0xbfb8aa3b, v71
	v_exp_f32_e32 v78, v78
	s_nop 0
	v_add_f32_e32 v78, 1.0, v78
	v_rcp_f32_e32 v87, v78
	s_nop 0
	v_pk_mul_f32 v[70:71], v[70:71], v[86:87]
	s_nop 0
	v_pk_mul_f32 v[70:71], v[70:71], v[66:67]
	v_mul_f32_e32 v67, 0xbfb8aa3b, v72
	v_exp_f32_e32 v67, v67
	v_mul_f32_e32 v66, 0xbfb8aa3b, v80
	v_exp_f32_e32 v66, v66
	v_add_f32_e32 v67, 1.0, v67
	v_rcp_f32_e32 v78, v67
	v_mul_f32_e32 v67, 0xbfb8aa3b, v81
	v_exp_f32_e32 v67, v67
	v_add_f32_e32 v66, 1.0, v66
	v_rcp_f32_e32 v66, v66
	v_add_f32_e32 v67, 1.0, v67
	v_rcp_f32_e32 v67, v67
	s_nop 0
	v_pk_mul_f32 v[66:67], v[80:81], v[66:67]
	s_nop 0
	v_pk_mul_f32 v[76:77], v[66:67], v[76:77]
	v_mul_f32_e32 v66, 0xbfb8aa3b, v73
	v_exp_f32_e32 v66, v66
	s_nop 0
	v_add_f32_e32 v66, 1.0, v66
	v_rcp_f32_e32 v79, v66
	s_nop 0
	v_pk_mul_f32 v[66:67], v[72:73], v[78:79]
	s_nop 0
	v_pk_mul_f32 v[72:73], v[66:67], v[68:69]
	v_lshl_add_u64 v[78:79], v[82:83], 0, v[114:115]
	v_cvt_pk_bf16_f32 v66, v74, v75
	v_cvt_pk_bf16_f32 v67, v76, v77
	v_cvt_pk_bf16_f32 v68, v70, v71
	v_cvt_pk_bf16_f32 v69, v72, v73
	global_store_dwordx4 v[78:79], v[66:69], off sc1
	s_nop 1
	v_mul_f32_e32 v69, 0xbfb8aa3b, v54
	v_exp_f32_e32 v69, v69
	v_mul_f32_e32 v68, 0xbfb8aa3b, v62
	v_exp_f32_e32 v68, v68
	v_add_u32_e32 v66, 0x80, v142
	v_add_f32_e32 v69, 1.0, v69
	v_rcp_f32_e32 v70, v69
	v_mul_f32_e32 v69, 0xbfb8aa3b, v63
	v_exp_f32_e32 v69, v69
	v_add_f32_e32 v68, 1.0, v68
	v_rcp_f32_e32 v68, v68
	v_mad_i64_i32 v[66:67], s[60:61], v66, s24, v[136:137]
	v_add_f32_e32 v69, 1.0, v69
	v_rcp_f32_e32 v69, v69
	s_nop 0
	v_pk_mul_f32 v[62:63], v[62:63], v[68:69]
	s_nop 0
	v_pk_mul_f32 v[58:59], v[62:63], v[58:59]
	v_mul_f32_e32 v62, 0xbfb8aa3b, v55
	v_exp_f32_e32 v62, v62
	s_nop 0
	v_add_f32_e32 v62, 1.0, v62
	v_rcp_f32_e32 v71, v62
	s_nop 0
	v_pk_mul_f32 v[54:55], v[54:55], v[70:71]
	s_nop 0
	v_pk_mul_f32 v[54:55], v[54:55], v[50:51]
	v_mul_f32_e32 v51, 0xbfb8aa3b, v56
	v_exp_f32_e32 v51, v51
	v_mul_f32_e32 v50, 0xbfb8aa3b, v64
	v_exp_f32_e32 v50, v50
	v_add_f32_e32 v51, 1.0, v51
	v_rcp_f32_e32 v62, v51
	v_mul_f32_e32 v51, 0xbfb8aa3b, v65
	v_exp_f32_e32 v51, v51
	v_add_f32_e32 v50, 1.0, v50
	v_rcp_f32_e32 v50, v50
	v_add_f32_e32 v51, 1.0, v51
	v_rcp_f32_e32 v51, v51
	s_nop 0
	v_pk_mul_f32 v[50:51], v[64:65], v[50:51]
	s_nop 0
	v_pk_mul_f32 v[60:61], v[50:51], v[60:61]
	v_mul_f32_e32 v50, 0xbfb8aa3b, v57
	v_exp_f32_e32 v50, v50
	s_nop 0
	v_add_f32_e32 v50, 1.0, v50
	v_rcp_f32_e32 v63, v50
	s_nop 0
	v_pk_mul_f32 v[50:51], v[56:57], v[62:63]
	s_nop 0
	v_pk_mul_f32 v[56:57], v[50:51], v[52:53]
	v_lshl_add_u64 v[62:63], v[66:67], 0, v[114:115]
	v_cvt_pk_bf16_f32 v50, v58, v59
	v_cvt_pk_bf16_f32 v51, v60, v61
	v_cvt_pk_bf16_f32 v52, v54, v55
	v_cvt_pk_bf16_f32 v53, v56, v57
	global_store_dwordx4 v[62:63], v[50:53], off sc1
	s_nop 1
	v_mul_f32_e32 v53, 0xbfb8aa3b, v38
	v_exp_f32_e32 v53, v53
	v_mul_f32_e32 v52, 0xbfb8aa3b, v46
	v_exp_f32_e32 v52, v52
	v_add_u32_e32 v50, 0x90, v142
	v_add_f32_e32 v53, 1.0, v53
	v_rcp_f32_e32 v54, v53
	v_mul_f32_e32 v53, 0xbfb8aa3b, v47
	v_exp_f32_e32 v53, v53
	v_add_f32_e32 v52, 1.0, v52
	v_rcp_f32_e32 v52, v52
	v_mad_i64_i32 v[50:51], s[60:61], v50, s24, v[136:137]
	v_add_f32_e32 v53, 1.0, v53
	v_rcp_f32_e32 v53, v53
	s_nop 0
	v_pk_mul_f32 v[46:47], v[46:47], v[52:53]
	s_nop 0
	v_pk_mul_f32 v[42:43], v[46:47], v[42:43]
	v_mul_f32_e32 v46, 0xbfb8aa3b, v39
	v_exp_f32_e32 v46, v46
	s_nop 0
	v_add_f32_e32 v46, 1.0, v46
	v_rcp_f32_e32 v55, v46
	s_nop 0
	v_pk_mul_f32 v[38:39], v[38:39], v[54:55]
	s_nop 0
	v_pk_mul_f32 v[38:39], v[38:39], v[34:35]
	v_mul_f32_e32 v35, 0xbfb8aa3b, v40
	v_exp_f32_e32 v35, v35
	v_mul_f32_e32 v34, 0xbfb8aa3b, v48
	v_exp_f32_e32 v34, v34
	v_add_f32_e32 v35, 1.0, v35
	v_rcp_f32_e32 v46, v35
	v_mul_f32_e32 v35, 0xbfb8aa3b, v49
; __device__ __forceinline__ unsigned pk2(float lo, float hi) { f32x2 v = {lo, hi}; bf16x2_t b = __builtin_convertvector(v, bf16x2_t); return __builtin_bit_cast(unsigned, b); }
; __device__ __forceinline__ float siluf_(float x) { return x * sigmoidf_(x); }
; #define PG8_BAR __builtin_amdgcn_s_barrier()
; template <class Epi, class Sched>
; __device__ __forceinline__ void gemm_phase(LAS unsigned char* lds, const Gemm g, const Sched& S, const Epi& E) {
;     ...
;         if (!has_next) break;
; #pragma unroll
;         for (int a = 0; a < 2; ++a)
; #pragma unroll
;             for (int b = 0; b < 2; ++b)
; #pragma unroll
;                 for (int m = 0; m < 4; ++m)
; #pragma unroll
;                     for (int n = 0; n < 2; ++n) acc[a][b][m][n] = (f32x4){0.f, 0.f, 0.f, 0.f};
;         cur = nxt; cA = nA; cB = nB; ++ui;
;         if (wr == 1) PG8_BAR;
;     __device__ __forceinline__ void operator()(const f32x4 (&acc)[2][2][4][2], const Unit& u, int wr, int wc, int fr, int fq) const {
;         const int row0 = u.pm * BM + wr * 64 + fr, col0 = u.pn * 128 + wc * 32 + 8 * fq;
; #pragma unroll
;         for (int ai = 0; ai < 2; ++ai)
; #pragma unroll
;             for (int m = 0; m < 4; ++m) {
;                 bf16_t* rowp = O + (size_t)(row0 + ai * HALF + m * 16) * FF + col0;
;                 const f32x4 g0 = acc[ai][0][m][0], g1 = acc[ai][0][m][1], u0 = acc[ai][1][m][0], u1 = acc[ai][1][m][1];
;                 f32x4 h0, h1;
; #pragma unroll
;                 for (int j = 0; j < 4; ++j) { h0[j] = siluf_(g0[j]) * u0[j]; h1[j] = siluf_(g1[j]) * u1[j]; }
;                 u32x4 w; w.x = pk2(h0[0], h0[1]); w.y = pk2(h0[2], h0[3]); w.z = pk2(h1[0], h1[1]); w.w = pk2(h1[2], h1[3]);
;                 *(u32x4*)rowp = w;
;             }
;     }
	v_exp_f32_e32 v35, v35
	v_add_f32_e32 v34, 1.0, v34
	v_rcp_f32_e32 v34, v34
	v_add_f32_e32 v35, 1.0, v35
	v_rcp_f32_e32 v35, v35
	s_nop 0
	v_pk_mul_f32 v[34:35], v[48:49], v[34:35]
	s_nop 0
	v_pk_mul_f32 v[44:45], v[34:35], v[44:45]
	v_mul_f32_e32 v34, 0xbfb8aa3b, v41
	v_exp_f32_e32 v34, v34
	s_nop 0
	v_add_f32_e32 v34, 1.0, v34
	v_rcp_f32_e32 v47, v34
	s_nop 0
	v_pk_mul_f32 v[34:35], v[40:41], v[46:47]
	s_nop 0
	v_pk_mul_f32 v[40:41], v[34:35], v[36:37]
	v_lshl_add_u64 v[46:47], v[50:51], 0, v[114:115]
	v_cvt_pk_bf16_f32 v34, v42, v43
	v_cvt_pk_bf16_f32 v35, v44, v45
	v_cvt_pk_bf16_f32 v36, v38, v39
	v_cvt_pk_bf16_f32 v37, v40, v41
	global_store_dwordx4 v[46:47], v[34:37], off sc1
	s_nop 1
	v_mul_f32_e32 v37, 0xbfb8aa3b, v22
	v_exp_f32_e32 v37, v37
	v_mul_f32_e32 v36, 0xbfb8aa3b, v30
	v_exp_f32_e32 v36, v36
	v_add_u32_e32 v34, 0xa0, v142
	v_add_f32_e32 v37, 1.0, v37
	v_rcp_f32_e32 v38, v37
	v_mul_f32_e32 v37, 0xbfb8aa3b, v31
	v_exp_f32_e32 v37, v37
	v_add_f32_e32 v36, 1.0, v36
	v_rcp_f32_e32 v36, v36
	v_mad_i64_i32 v[34:35], s[60:61], v34, s24, v[136:137]
	v_add_f32_e32 v37, 1.0, v37
	v_rcp_f32_e32 v37, v37
	s_nop 0
	v_pk_mul_f32 v[30:31], v[30:31], v[36:37]
	s_nop 0
	v_pk_mul_f32 v[26:27], v[30:31], v[26:27]
	v_mul_f32_e32 v30, 0xbfb8aa3b, v23
	v_exp_f32_e32 v30, v30
	s_nop 0
	v_add_f32_e32 v30, 1.0, v30
	v_rcp_f32_e32 v39, v30
	s_nop 0
	v_pk_mul_f32 v[22:23], v[22:23], v[38:39]
	s_nop 0
	v_pk_mul_f32 v[22:23], v[22:23], v[18:19]
	v_mul_f32_e32 v19, 0xbfb8aa3b, v24
	v_exp_f32_e32 v19, v19
	v_mul_f32_e32 v18, 0xbfb8aa3b, v32
	v_exp_f32_e32 v18, v18
	v_add_f32_e32 v19, 1.0, v19
	v_rcp_f32_e32 v30, v19
	v_mul_f32_e32 v19, 0xbfb8aa3b, v33
	v_exp_f32_e32 v19, v19
	v_add_f32_e32 v18, 1.0, v18
	v_rcp_f32_e32 v18, v18
	v_add_f32_e32 v19, 1.0, v19
	v_rcp_f32_e32 v19, v19
	s_nop 0
	v_pk_mul_f32 v[18:19], v[32:33], v[18:19]
	s_nop 0
	v_pk_mul_f32 v[28:29], v[18:19], v[28:29]
	v_mul_f32_e32 v18, 0xbfb8aa3b, v25
	v_exp_f32_e32 v18, v18
	s_nop 0
	v_add_f32_e32 v18, 1.0, v18
	v_rcp_f32_e32 v31, v18
	s_nop 0
	v_pk_mul_f32 v[18:19], v[24:25], v[30:31]
	s_nop 0
	v_pk_mul_f32 v[24:25], v[18:19], v[20:21]
	v_lshl_add_u64 v[30:31], v[34:35], 0, v[114:115]
	v_cvt_pk_bf16_f32 v18, v26, v27
	v_cvt_pk_bf16_f32 v19, v28, v29
	v_cvt_pk_bf16_f32 v20, v22, v23
	v_cvt_pk_bf16_f32 v21, v24, v25
	global_store_dwordx4 v[30:31], v[18:21], off sc1
	s_nop 1
	v_mul_f32_e32 v21, 0xbfb8aa3b, v6
	v_exp_f32_e32 v21, v21
	v_mul_f32_e32 v20, 0xbfb8aa3b, v14
	v_exp_f32_e32 v20, v20
	v_add_u32_e32 v18, 0xb0, v142
	v_add_f32_e32 v21, 1.0, v21
	v_rcp_f32_e32 v22, v21
	v_mul_f32_e32 v21, 0xbfb8aa3b, v15
	v_exp_f32_e32 v21, v21
	v_add_f32_e32 v20, 1.0, v20
	v_rcp_f32_e32 v20, v20
	v_mad_i64_i32 v[18:19], s[60:61], v18, s24, v[136:137]
	v_add_f32_e32 v21, 1.0, v21
	v_rcp_f32_e32 v21, v21
	s_mov_b64 s[60:61], -1
	v_pk_mul_f32 v[14:15], v[14:15], v[20:21]
	s_nop 0
	v_pk_mul_f32 v[10:11], v[14:15], v[10:11]
	v_mul_f32_e32 v14, 0xbfb8aa3b, v7
	v_exp_f32_e32 v14, v14
	s_nop 0
	v_add_f32_e32 v14, 1.0, v14
	v_rcp_f32_e32 v23, v14
	s_nop 0
	v_pk_mul_f32 v[6:7], v[6:7], v[22:23]
	s_nop 0
	v_pk_mul_f32 v[6:7], v[6:7], v[2:3]
	v_mul_f32_e32 v3, 0xbfb8aa3b, v8
	v_exp_f32_e32 v3, v3
	v_mul_f32_e32 v2, 0xbfb8aa3b, v16
	v_exp_f32_e32 v2, v2
	v_add_f32_e32 v3, 1.0, v3
	v_rcp_f32_e32 v14, v3
	v_mul_f32_e32 v3, 0xbfb8aa3b, v17
	v_exp_f32_e32 v3, v3
	v_add_f32_e32 v2, 1.0, v2
	v_rcp_f32_e32 v2, v2
	v_add_f32_e32 v3, 1.0, v3
	v_rcp_f32_e32 v3, v3
	s_nop 0
	v_pk_mul_f32 v[2:3], v[16:17], v[2:3]
	s_nop 0
	v_pk_mul_f32 v[12:13], v[2:3], v[12:13]
	v_mul_f32_e32 v2, 0xbfb8aa3b, v9
	v_exp_f32_e32 v2, v2
	s_nop 0
	v_add_f32_e32 v2, 1.0, v2
	v_rcp_f32_e32 v15, v2
	s_nop 0
	v_pk_mul_f32 v[2:3], v[8:9], v[14:15]
	s_nop 0
	v_pk_mul_f32 v[8:9], v[2:3], v[4:5]
	v_lshl_add_u64 v[14:15], v[18:19], 0, v[114:115]
	v_cvt_pk_bf16_f32 v2, v10, v11
	v_cvt_pk_bf16_f32 v3, v12, v13
	v_cvt_pk_bf16_f32 v4, v6, v7
	v_cvt_pk_bf16_f32 v5, v8, v9
	global_store_dwordx4 v[14:15], v[2:5], off sc1
	s_cbranch_vccnz .LBB0_47
	s_andn2_b64 vcc, exec, s[14:15]
	s_cbranch_vccnz .LBB0_46
	s_barrier
	s_branch .LBB0_46

; __device__ __forceinline__ unsigned pk2(float lo, float hi) { f32x2 v = {lo, hi}; bf16x2_t b = __builtin_convertvector(v, bf16x2_t); return __builtin_bit_cast(unsigned, b); }
;     __device__ __forceinline__ void operator()(const f32x4 (&acc)[2][2][4][2], const Unit& u, int wr, int wc, int fr, int fq) const {
;     ...
;         } else {
;             const int col0 = u.pn * BM + wc * 32 + 8 * fq;
; #pragma unroll
;             for (int ai = 0; ai < 2; ++ai)
; #pragma unroll
;                 for (int m = 0; m < 4; ++m) {
;                     bf16_t* rowp = P + (size_t)(row0 + ai * HALF + m * 16) * INC + col0;
; #pragma unroll
;                     for (int bj = 0; bj < 2; ++bj) {
;                         const f32x4 v0 = acc[ai][bj][m][0], v1 = acc[ai][bj][m][1];
;                         u32x4 w; w.x = pk2(v0[0], v0[1]); w.y = pk2(v0[2], v0[3]); w.z = pk2(v1[0], v1[1]); w.w = pk2(v1[2], v1[3]);
;                         *(u32x4*)(rowp + bj * HALF) = w;
;                     }
;                 }
.LBB0_159:
	v_lshl_add_u32 v143, s66, 8, v165
	s_mov_b64 s[66:67], -1
	s_cmp_gt_i32 s33, 7
	v_or_b32_e32 v179, 16, v143
	v_or_b32_e32 v178, 32, v143
	v_or_b32_e32 v177, 48, v143
	v_add_u32_e32 v176, 0x80, v143
	v_add_u32_e32 v175, 0x90, v143
	v_add_u32_e32 v174, 0xa0, v143
	v_add_u32_e32 v173, 0xb0, v143
	s_cbranch_scc0 .LBB0_162
	v_mov_b64_e32 v[180:181], s[40:41]
	s_movk_i32 s49, 0x3800
	v_mad_i64_i32 v[166:167], s[66:67], v143, s49, v[180:181]
	v_lshl_or_b32 v0, s33, 9, v172
	v_lshl_add_u64 v[182:183], v[166:167], 0, v[0:1]
	v_cvt_pk_bf16_f32 v166, v126, v127
	v_cvt_pk_bf16_f32 v167, v128, v129
	v_cvt_pk_bf16_f32 v168, v122, v123
	v_cvt_pk_bf16_f32 v169, v124, v125
	global_store_dwordx4 v[182:183], v[166:169], off sc1
	s_nop 1
	v_cvt_pk_bf16_f32 v166, v118, v119
	v_cvt_pk_bf16_f32 v167, v120, v121
	v_cvt_pk_bf16_f32 v168, v114, v115
	v_cvt_pk_bf16_f32 v169, v116, v117
	global_store_dwordx4 v[182:183], v[166:169], off offset:256 sc1
	s_nop 1
	v_mad_i64_i32 v[166:167], s[66:67], v179, s49, v[180:181]
	v_lshl_add_u64 v[182:183], v[166:167], 0, v[0:1]
	v_cvt_pk_bf16_f32 v166, v110, v111
	v_cvt_pk_bf16_f32 v167, v112, v113
	v_cvt_pk_bf16_f32 v168, v106, v107
	v_cvt_pk_bf16_f32 v169, v108, v109
	global_store_dwordx4 v[182:183], v[166:169], off sc1
	s_nop 1
	v_cvt_pk_bf16_f32 v166, v102, v103
	v_cvt_pk_bf16_f32 v167, v104, v105
	v_cvt_pk_bf16_f32 v168, v98, v99
	v_cvt_pk_bf16_f32 v169, v100, v101
	global_store_dwordx4 v[182:183], v[166:169], off offset:256 sc1
	s_nop 1
	v_mad_i64_i32 v[166:167], s[66:67], v178, s49, v[180:181]
	v_lshl_add_u64 v[182:183], v[166:167], 0, v[0:1]
	v_cvt_pk_bf16_f32 v166, v94, v95
	v_cvt_pk_bf16_f32 v167, v96, v97
	v_cvt_pk_bf16_f32 v168, v90, v91
	v_cvt_pk_bf16_f32 v169, v92, v93
	global_store_dwordx4 v[182:183], v[166:169], off sc1
	s_nop 1
	v_cvt_pk_bf16_f32 v166, v86, v87
	v_cvt_pk_bf16_f32 v167, v88, v89
	v_cvt_pk_bf16_f32 v168, v82, v83
	v_cvt_pk_bf16_f32 v169, v84, v85
	global_store_dwordx4 v[182:183], v[166:169], off offset:256 sc1
	s_nop 1
	v_mad_i64_i32 v[166:167], s[66:67], v177, s49, v[180:181]
	v_lshl_add_u64 v[182:183], v[166:167], 0, v[0:1]
	v_cvt_pk_bf16_f32 v166, v78, v79
	v_cvt_pk_bf16_f32 v167, v80, v81
	v_cvt_pk_bf16_f32 v168, v74, v75
	v_cvt_pk_bf16_f32 v169, v76, v77
	global_store_dwordx4 v[182:183], v[166:169], off sc1
	s_nop 1
	v_cvt_pk_bf16_f32 v166, v70, v71
	v_cvt_pk_bf16_f32 v167, v72, v73
	v_cvt_pk_bf16_f32 v168, v66, v67
	v_cvt_pk_bf16_f32 v169, v68, v69
	global_store_dwordx4 v[182:183], v[166:169], off offset:256 sc1
	s_nop 1
	v_mad_i64_i32 v[166:167], s[66:67], v176, s49, v[180:181]
	v_lshl_add_u64 v[182:183], v[166:167], 0, v[0:1]
	v_cvt_pk_bf16_f32 v166, v62, v63
	v_cvt_pk_bf16_f32 v167, v64, v65
	v_cvt_pk_bf16_f32 v168, v58, v59
	v_cvt_pk_bf16_f32 v169, v60, v61
	global_store_dwordx4 v[182:183], v[166:169], off sc1
	s_nop 1
	v_cvt_pk_bf16_f32 v166, v54, v55
	v_cvt_pk_bf16_f32 v167, v56, v57
	v_cvt_pk_bf16_f32 v168, v50, v51
	v_cvt_pk_bf16_f32 v169, v52, v53
	global_store_dwordx4 v[182:183], v[166:169], off offset:256 sc1
	s_nop 1
	v_mad_i64_i32 v[166:167], s[66:67], v175, s49, v[180:181]
	v_lshl_add_u64 v[182:183], v[166:167], 0, v[0:1]
	v_cvt_pk_bf16_f32 v166, v46, v47
	v_cvt_pk_bf16_f32 v167, v48, v49
	v_cvt_pk_bf16_f32 v168, v42, v43
	v_cvt_pk_bf16_f32 v169, v44, v45
	global_store_dwordx4 v[182:183], v[166:169], off sc1
	s_nop 1
	v_cvt_pk_bf16_f32 v166, v38, v39
	v_cvt_pk_bf16_f32 v167, v40, v41
	v_cvt_pk_bf16_f32 v168, v34, v35
	v_cvt_pk_bf16_f32 v169, v36, v37
	global_store_dwordx4 v[182:183], v[166:169], off offset:256 sc1
	s_nop 1
	v_mad_i64_i32 v[166:167], s[66:67], v174, s49, v[180:181]
	v_lshl_add_u64 v[182:183], v[166:167], 0, v[0:1]
	v_cvt_pk_bf16_f32 v166, v30, v31
	v_cvt_pk_bf16_f32 v167, v32, v33
	v_cvt_pk_bf16_f32 v168, v26, v27
	v_cvt_pk_bf16_f32 v169, v28, v29
	global_store_dwordx4 v[182:183], v[166:169], off sc1
	s_nop 1
	v_cvt_pk_bf16_f32 v166, v22, v23
	v_cvt_pk_bf16_f32 v167, v24, v25
	v_cvt_pk_bf16_f32 v168, v18, v19
	v_cvt_pk_bf16_f32 v169, v20, v21
	global_store_dwordx4 v[182:183], v[166:169], off offset:256 sc1
	s_nop 1
	v_mad_i64_i32 v[166:167], s[66:67], v173, s49, v[180:181]
	v_lshl_add_u64 v[180:181], v[166:167], 0, v[0:1]
	v_cvt_pk_bf16_f32 v166, v14, v15
	v_cvt_pk_bf16_f32 v167, v16, v17
	v_cvt_pk_bf16_f32 v168, v10, v11
	v_cvt_pk_bf16_f32 v169, v12, v13
	global_store_dwordx4 v[180:181], v[166:169], off sc1
	s_nop 1
	v_cvt_pk_bf16_f32 v166, v6, v7
	v_cvt_pk_bf16_f32 v167, v8, v9
	v_cvt_pk_bf16_f32 v168, v2, v3
	v_cvt_pk_bf16_f32 v169, v4, v5
	global_store_dwordx4 v[180:181], v[166:169], off offset:256 sc1
	s_cbranch_execz .LBB0_163

; __device__ __forceinline__ unsigned pk2(float lo, float hi) { f32x2 v = {lo, hi}; bf16x2_t b = __builtin_convertvector(v, bf16x2_t); return __builtin_bit_cast(unsigned, b); }
; __device__ __forceinline__ void swap16(unsigned& a, unsigned& b) { auto r = __builtin_amdgcn_permlane16_swap(a, b, false, false); a = r[0]; b = r[1]; }
;     __device__ __forceinline__ void operator()(const f32x4 (&acc)[2][2][4][2], const Unit& u, int wr, int wc, int fr, int fq) const {
;     ...
;         if (u.pn < 8) {
; #pragma unroll
;             for (int ai = 0; ai < 2; ++ai)
; #pragma unroll
;                 for (int m = 0; m < 4; ++m) {
;                     const int row = row0 + ai * HALF + m * 16, pos = row & (SEQ - 1);
; #pragma unroll
;                     for (int bj = 0; bj < 2; ++bj) {
;                         const int g = 4 * bj + wc, hl = g >> 1, d0 = (g & 1) * 16 + 4 * fq;
;                         const f32x4 c = *(const f32x4*)(cosT + pos * 32 + d0), s = *(const f32x4*)(sinT + pos * 32 + d0);
;                         const f32x4 x1 = acc[ai][bj][m][0], x2 = acc[ai][bj][m][1];
;                         const float qs = (u.pn < 4) ? 0.125f * 1.4426950408889634f : 1.0f;
;                         const f32x4 o1 = (x1 * c - x2 * s) * qs, o2 = (x2 * c + x1 * s) * qs;
;                         bf16_t* p = P + (size_t)row * INC + u.pn * BM + hl * 64 + d0;
;                         unsigned a0 = pk2(o1[0], o1[1]), a1 = pk2(o1[2], o1[3]), b0 = pk2(o2[0], o2[1]), b1 = pk2(o2[2], o2[3]);
;                         swap16(a0, b0); swap16(a1, b1);
;                         *(u32x4*)(p + ((fq & 1) ? 28 : 0)) = (u32x4){a0, a1, b0, b1};
;                         asm volatile("" ::: "memory");
;                     }
;                 }
.LBB0_163:
	s_cmp_lt_i32 s33, 4
	s_cselect_b64 vcc, -1, 0
	v_mov_b32_e32 v0, 0x3e38aa3b
	v_cndmask_b32_e32 v164, 1.0, v0, vcc
	v_lshlrev_b32_e32 v0, 7, v143
	v_and_b32_e32 v0, 0xfe780, v0
	v_lshl_add_u64 v[166:167], v[134:135], 0, v[0:1]
	v_lshl_add_u64 v[168:169], v[136:137], 0, v[0:1]
	global_load_dwordx4 v[180:183], v[166:167], off
	global_load_dwordx4 v[184:187], v[168:169], off
	s_lshl_b32 s66, s33, 8
	s_ashr_i32 s67, s66, 31
	s_movk_i32 s33, 0x3800
	s_lshl_b64 s[66:67], s[66:67], 1
	v_mov_b32_e32 v145, v1
	v_lshlrev_b32_e32 v0, 7, v179
	v_and_b32_e32 v0, 0xfef80, v0
	s_waitcnt vmcnt(0)
	v_pk_mul_f32 v[190:191], v[122:123], v[184:185]
	v_pk_mul_f32 v[188:189], v[124:125], v[186:187]
	v_pk_fma_f32 v[190:191], v[126:127], v[180:181], v[190:191] neg_lo:[0,0,1] neg_hi:[0,0,1]
	v_pk_mul_f32 v[126:127], v[126:127], v[184:185]
	v_pk_fma_f32 v[188:189], v[128:129], v[182:183], v[188:189] neg_lo:[0,0,1] neg_hi:[0,0,1]
	v_pk_mul_f32 v[128:129], v[128:129], v[186:187]
	v_pk_fma_f32 v[122:123], v[122:123], v[180:181], v[126:127]
	v_pk_fma_f32 v[124:125], v[124:125], v[182:183], v[128:129]
	v_pk_mul_f32 v[126:127], v[164:165], v[122:123] op_sel_hi:[0,1]
	v_mov_b64_e32 v[122:123], s[40:41]
	v_pk_mul_f32 v[128:129], v[164:165], v[124:125] op_sel_hi:[0,1]
	v_mad_i64_i32 v[124:125], s[68:69], v143, s33, v[122:123]
	v_lshl_add_u64 v[124:125], v[124:125], 0, s[66:67]
	v_pk_mul_f32 v[188:189], v[164:165], v[188:189] op_sel_hi:[0,1]
	v_pk_mul_f32 v[190:191], v[164:165], v[190:191] op_sel_hi:[0,1]
	v_lshl_add_u64 v[124:125], v[124:125], 0, s[36:37]
	v_mov_b32_e32 v143, v1
	v_lshl_add_u64 v[180:181], v[124:125], 0, v[142:143]
	v_cvt_pk_bf16_f32 v124, v190, v191
	v_cvt_pk_bf16_f32 v125, v188, v189
	v_cvt_pk_bf16_f32 v126, v126, v127
	v_cvt_pk_bf16_f32 v127, v128, v129
	s_nop 0
	v_permlane16_swap_b32_e32 v124, v126
	v_permlane16_swap_b32_e32 v125, v127
	v_lshl_add_u64 v[128:129], v[180:181], 0, v[144:145]
	global_store_dwordx4 v[128:129], v[124:127], off sc1
	global_load_dwordx4 v[124:127], v[166:167], off
	s_nop 0
	global_load_dwordx4 v[166:169], v[168:169], off
	s_waitcnt vmcnt(0)
	v_pk_mul_f32 v[180:181], v[116:117], v[168:169]
	v_pk_mul_f32 v[182:183], v[114:115], v[166:167]
	v_pk_fma_f32 v[180:181], v[120:121], v[126:127], v[180:181] neg_lo:[0,0,1] neg_hi:[0,0,1]
	v_pk_fma_f32 v[182:183], v[118:119], v[124:125], v[182:183] neg_lo:[0,0,1] neg_hi:[0,0,1]
	v_pk_mul_f32 v[120:121], v[120:121], v[168:169]
	v_pk_mul_f32 v[118:119], v[118:119], v[166:167]
	v_pk_fma_f32 v[116:117], v[116:117], v[126:127], v[120:121]
	v_pk_fma_f32 v[114:115], v[114:115], v[124:125], v[118:119]
	v_pk_mul_f32 v[180:181], v[164:165], v[180:181] op_sel_hi:[0,1]
	v_pk_mul_f32 v[182:183], v[164:165], v[182:183] op_sel_hi:[0,1]
	v_pk_mul_f32 v[118:119], v[164:165], v[116:117] op_sel_hi:[0,1]
	v_pk_mul_f32 v[116:117], v[164:165], v[114:115] op_sel_hi:[0,1]
	v_cvt_pk_bf16_f32 v114, v182, v183
	v_cvt_pk_bf16_f32 v115, v180, v181
	v_cvt_pk_bf16_f32 v116, v116, v117
	v_cvt_pk_bf16_f32 v117, v118, v119
	s_nop 0
	v_permlane16_swap_b32_e32 v114, v116
	v_permlane16_swap_b32_e32 v115, v117
	global_store_dwordx4 v[128:129], v[114:117], off offset:256 sc1
	s_nop 1
	v_lshl_add_u64 v[114:115], v[134:135], 0, v[0:1]
	v_lshl_add_u64 v[116:117], v[136:137], 0, v[0:1]
	global_load_dwordx4 v[118:121], v[114:115], off
	global_load_dwordx4 v[124:127], v[116:117], off
	v_lshlrev_b32_e32 v0, 7, v178
	v_and_b32_e32 v0, 0xff780, v0
	s_waitcnt vmcnt(0)
	v_pk_mul_f32 v[128:129], v[108:109], v[126:127]
	v_pk_mul_f32 v[166:167], v[106:107], v[124:125]
	v_pk_fma_f32 v[128:129], v[112:113], v[120:121], v[128:129] neg_lo:[0,0,1] neg_hi:[0,0,1]
	v_pk_fma_f32 v[166:167], v[110:111], v[118:119], v[166:167] neg_lo:[0,0,1] neg_hi:[0,0,1]
	v_pk_mul_f32 v[112:113], v[112:113], v[126:127]
	v_pk_mul_f32 v[110:111], v[110:111], v[124:125]
	v_pk_fma_f32 v[108:109], v[108:109], v[120:121], v[112:113]
	v_pk_fma_f32 v[106:107], v[106:107], v[118:119], v[110:111]
	v_pk_mul_f32 v[110:111], v[164:165], v[108:109] op_sel_hi:[0,1]
	v_pk_mul_f32 v[108:109], v[164:165], v[106:107] op_sel_hi:[0,1]
	v_mad_i64_i32 v[106:107], s[68:69], v179, s33, v[122:123]
	v_lshl_add_u64 v[106:107], v[106:107], 0, s[66:67]
	v_pk_mul_f32 v[128:129], v[164:165], v[128:129] op_sel_hi:[0,1]
	v_pk_mul_f32 v[166:167], v[164:165], v[166:167] op_sel_hi:[0,1]
	v_lshl_add_u64 v[106:107], v[106:107], 0, s[36:37]
	v_lshl_add_u64 v[112:113], v[106:107], 0, v[142:143]
	v_cvt_pk_bf16_f32 v106, v166, v167
	v_cvt_pk_bf16_f32 v107, v128, v129
	v_cvt_pk_bf16_f32 v108, v108, v109
	v_cvt_pk_bf16_f32 v109, v110, v111
	s_nop 0
	v_permlane16_swap_b32_e32 v106, v108
	v_permlane16_swap_b32_e32 v107, v109
	v_lshl_add_u64 v[118:119], v[112:113], 0, v[144:145]
	global_store_dwordx4 v[118:119], v[106:109], off sc1
	global_load_dwordx4 v[106:109], v[114:115], off
	global_load_dwordx4 v[110:113], v[116:117], off
	s_waitcnt vmcnt(0)
	v_pk_mul_f32 v[114:115], v[100:101], v[112:113]
	v_pk_mul_f32 v[116:117], v[98:99], v[110:111]
	v_pk_fma_f32 v[114:115], v[104:105], v[108:109], v[114:115] neg_lo:[0,0,1] neg_hi:[0,0,1]
	v_pk_fma_f32 v[116:117], v[102:103], v[106:107], v[116:117] neg_lo:[0,0,1] neg_hi:[0,0,1]
	v_pk_mul_f32 v[104:105], v[104:105], v[112:113]
	v_pk_mul_f32 v[102:103], v[102:103], v[110:111]
	v_pk_fma_f32 v[100:101], v[100:101], v[108:109], v[104:105]
	v_pk_fma_f32 v[98:99], v[98:99], v[106:107], v[102:103]
	v_pk_mul_f32 v[114:115], v[164:165], v[114:115] op_sel_hi:[0,1]
	v_pk_mul_f32 v[116:117], v[164:165], v[116:117] op_sel_hi:[0,1]
	v_pk_mul_f32 v[102:103], v[164:165], v[100:101] op_sel_hi:[0,1]
	v_pk_mul_f32 v[100:101], v[164:165], v[98:99] op_sel_hi:[0,1]
	v_cvt_pk_bf16_f32 v98, v116, v117
	v_cvt_pk_bf16_f32 v99, v114, v115
	v_cvt_pk_bf16_f32 v100, v100, v101
	v_cvt_pk_bf16_f32 v101, v102, v103
	s_nop 0
	v_permlane16_swap_b32_e32 v98, v100
	v_permlane16_swap_b32_e32 v99, v101
	global_store_dwordx4 v[118:119], v[98:101], off offset:256 sc1
	s_nop 1
	v_lshl_add_u64 v[98:99], v[134:135], 0, v[0:1]
	v_lshl_add_u64 v[100:101], v[136:137], 0, v[0:1]
	global_load_dwordx4 v[102:105], v[98:99], off
	global_load_dwordx4 v[106:109], v[100:101], off
	v_lshlrev_b32_e32 v0, 7, v177
	v_and_b32_e32 v0, 0xfff80, v0
	s_waitcnt vmcnt(0)
; __device__ __forceinline__ unsigned pk2(float lo, float hi) { f32x2 v = {lo, hi}; bf16x2_t b = __builtin_convertvector(v, bf16x2_t); return __builtin_bit_cast(unsigned, b); }
; __device__ __forceinline__ void swap16(unsigned& a, unsigned& b) { auto r = __builtin_amdgcn_permlane16_swap(a, b, false, false); a = r[0]; b = r[1]; }
;     __device__ __forceinline__ void operator()(const f32x4 (&acc)[2][2][4][2], const Unit& u, int wr, int wc, int fr, int fq) const {
;     ...
;         if (u.pn < 8) {
; #pragma unroll
;             for (int ai = 0; ai < 2; ++ai)
; #pragma unroll
;                 for (int m = 0; m < 4; ++m) {
;                     const int row = row0 + ai * HALF + m * 16, pos = row & (SEQ - 1);
; #pragma unroll
;                     for (int bj = 0; bj < 2; ++bj) {
;                         const int g = 4 * bj + wc, hl = g >> 1, d0 = (g & 1) * 16 + 4 * fq;
;                         const f32x4 c = *(const f32x4*)(cosT + pos * 32 + d0), s = *(const f32x4*)(sinT + pos * 32 + d0);
;                         const f32x4 x1 = acc[ai][bj][m][0], x2 = acc[ai][bj][m][1];
;                         const float qs = (u.pn < 4) ? 0.125f * 1.4426950408889634f : 1.0f;
;                         const f32x4 o1 = (x1 * c - x2 * s) * qs, o2 = (x2 * c + x1 * s) * qs;
;                         bf16_t* p = P + (size_t)row * INC + u.pn * BM + hl * 64 + d0;
;                         unsigned a0 = pk2(o1[0], o1[1]), a1 = pk2(o1[2], o1[3]), b0 = pk2(o2[0], o2[1]), b1 = pk2(o2[2], o2[3]);
;                         swap16(a0, b0); swap16(a1, b1);
;                         *(u32x4*)(p + ((fq & 1) ? 28 : 0)) = (u32x4){a0, a1, b0, b1};
;                         asm volatile("" ::: "memory");
;                     }
;                 }
	v_pk_mul_f32 v[110:111], v[92:93], v[108:109]
	v_pk_mul_f32 v[112:113], v[90:91], v[106:107]
	v_pk_fma_f32 v[110:111], v[96:97], v[104:105], v[110:111] neg_lo:[0,0,1] neg_hi:[0,0,1]
	v_pk_fma_f32 v[112:113], v[94:95], v[102:103], v[112:113] neg_lo:[0,0,1] neg_hi:[0,0,1]
	v_pk_mul_f32 v[96:97], v[96:97], v[108:109]
	v_pk_mul_f32 v[94:95], v[94:95], v[106:107]
	v_pk_fma_f32 v[92:93], v[92:93], v[104:105], v[96:97]
	v_pk_fma_f32 v[90:91], v[90:91], v[102:103], v[94:95]
	v_pk_mul_f32 v[94:95], v[164:165], v[92:93] op_sel_hi:[0,1]
	v_pk_mul_f32 v[92:93], v[164:165], v[90:91] op_sel_hi:[0,1]
	v_mad_i64_i32 v[90:91], s[68:69], v178, s33, v[122:123]
	v_lshl_add_u64 v[90:91], v[90:91], 0, s[66:67]
	v_pk_mul_f32 v[110:111], v[164:165], v[110:111] op_sel_hi:[0,1]
	v_pk_mul_f32 v[112:113], v[164:165], v[112:113] op_sel_hi:[0,1]
	v_lshl_add_u64 v[90:91], v[90:91], 0, s[36:37]
	v_lshl_add_u64 v[96:97], v[90:91], 0, v[142:143]
	v_cvt_pk_bf16_f32 v90, v112, v113
	v_cvt_pk_bf16_f32 v91, v110, v111
	v_cvt_pk_bf16_f32 v92, v92, v93
	v_cvt_pk_bf16_f32 v93, v94, v95
	s_nop 0
	v_permlane16_swap_b32_e32 v90, v92
	v_permlane16_swap_b32_e32 v91, v93
	v_lshl_add_u64 v[102:103], v[96:97], 0, v[144:145]
	global_store_dwordx4 v[102:103], v[90:93], off sc1
	global_load_dwordx4 v[90:93], v[98:99], off
	global_load_dwordx4 v[94:97], v[100:101], off
	s_waitcnt vmcnt(0)
	v_pk_mul_f32 v[98:99], v[84:85], v[96:97]
	v_pk_mul_f32 v[100:101], v[82:83], v[94:95]
	v_pk_fma_f32 v[98:99], v[88:89], v[92:93], v[98:99] neg_lo:[0,0,1] neg_hi:[0,0,1]
	v_pk_fma_f32 v[100:101], v[86:87], v[90:91], v[100:101] neg_lo:[0,0,1] neg_hi:[0,0,1]
	v_pk_mul_f32 v[88:89], v[88:89], v[96:97]
	v_pk_mul_f32 v[86:87], v[86:87], v[94:95]
	v_pk_fma_f32 v[84:85], v[84:85], v[92:93], v[88:89]
	v_pk_fma_f32 v[82:83], v[82:83], v[90:91], v[86:87]
	v_pk_mul_f32 v[98:99], v[164:165], v[98:99] op_sel_hi:[0,1]
	v_pk_mul_f32 v[100:101], v[164:165], v[100:101] op_sel_hi:[0,1]
	v_pk_mul_f32 v[86:87], v[164:165], v[84:85] op_sel_hi:[0,1]
	v_pk_mul_f32 v[84:85], v[164:165], v[82:83] op_sel_hi:[0,1]
	v_cvt_pk_bf16_f32 v82, v100, v101
	v_cvt_pk_bf16_f32 v83, v98, v99
	v_cvt_pk_bf16_f32 v84, v84, v85
	v_cvt_pk_bf16_f32 v85, v86, v87
	s_nop 0
	v_permlane16_swap_b32_e32 v82, v84
	v_permlane16_swap_b32_e32 v83, v85
	global_store_dwordx4 v[102:103], v[82:85], off offset:256 sc1
	s_nop 1
	v_lshl_add_u64 v[82:83], v[134:135], 0, v[0:1]
	v_lshl_add_u64 v[84:85], v[136:137], 0, v[0:1]
	global_load_dwordx4 v[86:89], v[82:83], off
	global_load_dwordx4 v[90:93], v[84:85], off
	v_lshlrev_b32_e32 v0, 7, v176
	v_and_b32_e32 v0, 0xfe780, v0
	s_waitcnt vmcnt(0)
	v_pk_mul_f32 v[94:95], v[76:77], v[92:93]
	v_pk_mul_f32 v[96:97], v[74:75], v[90:91]
	v_pk_fma_f32 v[94:95], v[80:81], v[88:89], v[94:95] neg_lo:[0,0,1] neg_hi:[0,0,1]
	v_pk_fma_f32 v[96:97], v[78:79], v[86:87], v[96:97] neg_lo:[0,0,1] neg_hi:[0,0,1]
	v_pk_mul_f32 v[80:81], v[80:81], v[92:93]
	v_pk_mul_f32 v[78:79], v[78:79], v[90:91]
	v_pk_fma_f32 v[76:77], v[76:77], v[88:89], v[80:81]
	v_pk_fma_f32 v[74:75], v[74:75], v[86:87], v[78:79]
	v_pk_mul_f32 v[78:79], v[164:165], v[76:77] op_sel_hi:[0,1]
	v_pk_mul_f32 v[76:77], v[164:165], v[74:75] op_sel_hi:[0,1]
	v_mad_i64_i32 v[74:75], s[68:69], v177, s33, v[122:123]
	v_lshl_add_u64 v[74:75], v[74:75], 0, s[66:67]
	v_pk_mul_f32 v[94:95], v[164:165], v[94:95] op_sel_hi:[0,1]
	v_pk_mul_f32 v[96:97], v[164:165], v[96:97] op_sel_hi:[0,1]
	v_lshl_add_u64 v[74:75], v[74:75], 0, s[36:37]
	v_lshl_add_u64 v[80:81], v[74:75], 0, v[142:143]
	v_cvt_pk_bf16_f32 v74, v96, v97
	v_cvt_pk_bf16_f32 v75, v94, v95
	v_cvt_pk_bf16_f32 v76, v76, v77
	v_cvt_pk_bf16_f32 v77, v78, v79
	s_nop 0
	v_permlane16_swap_b32_e32 v74, v76
	v_permlane16_swap_b32_e32 v75, v77
	v_lshl_add_u64 v[86:87], v[80:81], 0, v[144:145]
	global_store_dwordx4 v[86:87], v[74:77], off sc1
	global_load_dwordx4 v[74:77], v[82:83], off
	global_load_dwordx4 v[78:81], v[84:85], off
	s_waitcnt vmcnt(0)
	v_pk_mul_f32 v[82:83], v[68:69], v[80:81]
	v_pk_mul_f32 v[84:85], v[66:67], v[78:79]
	v_pk_fma_f32 v[82:83], v[72:73], v[76:77], v[82:83] neg_lo:[0,0,1] neg_hi:[0,0,1]
	v_pk_fma_f32 v[84:85], v[70:71], v[74:75], v[84:85] neg_lo:[0,0,1] neg_hi:[0,0,1]
	v_pk_mul_f32 v[72:73], v[72:73], v[80:81]
	v_pk_mul_f32 v[70:71], v[70:71], v[78:79]
	v_pk_fma_f32 v[68:69], v[68:69], v[76:77], v[72:73]
	v_pk_fma_f32 v[66:67], v[66:67], v[74:75], v[70:71]
	v_pk_mul_f32 v[82:83], v[164:165], v[82:83] op_sel_hi:[0,1]
	v_pk_mul_f32 v[84:85], v[164:165], v[84:85] op_sel_hi:[0,1]
	v_pk_mul_f32 v[70:71], v[164:165], v[68:69] op_sel_hi:[0,1]
	v_pk_mul_f32 v[68:69], v[164:165], v[66:67] op_sel_hi:[0,1]
	v_cvt_pk_bf16_f32 v66, v84, v85
	v_cvt_pk_bf16_f32 v67, v82, v83
	v_cvt_pk_bf16_f32 v68, v68, v69
	v_cvt_pk_bf16_f32 v69, v70, v71
	s_nop 0
	v_permlane16_swap_b32_e32 v66, v68
	v_permlane16_swap_b32_e32 v67, v69
	global_store_dwordx4 v[86:87], v[66:69], off offset:256 sc1
	s_nop 1
	v_lshl_add_u64 v[66:67], v[134:135], 0, v[0:1]
	v_lshl_add_u64 v[68:69], v[136:137], 0, v[0:1]
	global_load_dwordx4 v[70:73], v[66:67], off
	global_load_dwordx4 v[74:77], v[68:69], off
	v_lshlrev_b32_e32 v0, 7, v175
	v_and_b32_e32 v0, 0xfef80, v0
	s_waitcnt vmcnt(0)
; __device__ __forceinline__ unsigned pk2(float lo, float hi) { f32x2 v = {lo, hi}; bf16x2_t b = __builtin_convertvector(v, bf16x2_t); return __builtin_bit_cast(unsigned, b); }
; __device__ __forceinline__ void swap16(unsigned& a, unsigned& b) { auto r = __builtin_amdgcn_permlane16_swap(a, b, false, false); a = r[0]; b = r[1]; }
;     __device__ __forceinline__ void operator()(const f32x4 (&acc)[2][2][4][2], const Unit& u, int wr, int wc, int fr, int fq) const {
;     ...
;         if (u.pn < 8) {
; #pragma unroll
;             for (int ai = 0; ai < 2; ++ai)
; #pragma unroll
;                 for (int m = 0; m < 4; ++m) {
;                     const int row = row0 + ai * HALF + m * 16, pos = row & (SEQ - 1);
; #pragma unroll
;                     for (int bj = 0; bj < 2; ++bj) {
;                         const int g = 4 * bj + wc, hl = g >> 1, d0 = (g & 1) * 16 + 4 * fq;
;                         const f32x4 c = *(const f32x4*)(cosT + pos * 32 + d0), s = *(const f32x4*)(sinT + pos * 32 + d0);
;                         const f32x4 x1 = acc[ai][bj][m][0], x2 = acc[ai][bj][m][1];
;                         const float qs = (u.pn < 4) ? 0.125f * 1.4426950408889634f : 1.0f;
;                         const f32x4 o1 = (x1 * c - x2 * s) * qs, o2 = (x2 * c + x1 * s) * qs;
;                         bf16_t* p = P + (size_t)row * INC + u.pn * BM + hl * 64 + d0;
;                         unsigned a0 = pk2(o1[0], o1[1]), a1 = pk2(o1[2], o1[3]), b0 = pk2(o2[0], o2[1]), b1 = pk2(o2[2], o2[3]);
;                         swap16(a0, b0); swap16(a1, b1);
;                         *(u32x4*)(p + ((fq & 1) ? 28 : 0)) = (u32x4){a0, a1, b0, b1};
;                         asm volatile("" ::: "memory");
;                     }
;                 }
	v_pk_mul_f32 v[78:79], v[60:61], v[76:77]
	v_pk_mul_f32 v[80:81], v[58:59], v[74:75]
	v_pk_fma_f32 v[78:79], v[64:65], v[72:73], v[78:79] neg_lo:[0,0,1] neg_hi:[0,0,1]
	v_pk_fma_f32 v[80:81], v[62:63], v[70:71], v[80:81] neg_lo:[0,0,1] neg_hi:[0,0,1]
	v_pk_mul_f32 v[64:65], v[64:65], v[76:77]
	v_pk_mul_f32 v[62:63], v[62:63], v[74:75]
	v_pk_fma_f32 v[60:61], v[60:61], v[72:73], v[64:65]
	v_pk_fma_f32 v[58:59], v[58:59], v[70:71], v[62:63]
	v_pk_mul_f32 v[62:63], v[164:165], v[60:61] op_sel_hi:[0,1]
	v_pk_mul_f32 v[60:61], v[164:165], v[58:59] op_sel_hi:[0,1]
	v_mad_i64_i32 v[58:59], s[68:69], v176, s33, v[122:123]
	v_lshl_add_u64 v[58:59], v[58:59], 0, s[66:67]
	v_pk_mul_f32 v[78:79], v[164:165], v[78:79] op_sel_hi:[0,1]
	v_pk_mul_f32 v[80:81], v[164:165], v[80:81] op_sel_hi:[0,1]
	v_lshl_add_u64 v[58:59], v[58:59], 0, s[36:37]
	v_lshl_add_u64 v[64:65], v[58:59], 0, v[142:143]
	v_cvt_pk_bf16_f32 v58, v80, v81
	v_cvt_pk_bf16_f32 v59, v78, v79
	v_cvt_pk_bf16_f32 v60, v60, v61
	v_cvt_pk_bf16_f32 v61, v62, v63
	s_nop 0
	v_permlane16_swap_b32_e32 v58, v60
	v_permlane16_swap_b32_e32 v59, v61
	v_lshl_add_u64 v[70:71], v[64:65], 0, v[144:145]
	global_store_dwordx4 v[70:71], v[58:61], off sc1
	global_load_dwordx4 v[58:61], v[66:67], off
	global_load_dwordx4 v[62:65], v[68:69], off
	s_waitcnt vmcnt(0)
	v_pk_mul_f32 v[66:67], v[52:53], v[64:65]
	v_pk_mul_f32 v[68:69], v[50:51], v[62:63]
	v_pk_fma_f32 v[66:67], v[56:57], v[60:61], v[66:67] neg_lo:[0,0,1] neg_hi:[0,0,1]
	v_pk_fma_f32 v[68:69], v[54:55], v[58:59], v[68:69] neg_lo:[0,0,1] neg_hi:[0,0,1]
	v_pk_mul_f32 v[56:57], v[56:57], v[64:65]
	v_pk_mul_f32 v[54:55], v[54:55], v[62:63]
	v_pk_fma_f32 v[52:53], v[52:53], v[60:61], v[56:57]
	v_pk_fma_f32 v[50:51], v[50:51], v[58:59], v[54:55]
	v_pk_mul_f32 v[66:67], v[164:165], v[66:67] op_sel_hi:[0,1]
	v_pk_mul_f32 v[68:69], v[164:165], v[68:69] op_sel_hi:[0,1]
	v_pk_mul_f32 v[54:55], v[164:165], v[52:53] op_sel_hi:[0,1]
	v_pk_mul_f32 v[52:53], v[164:165], v[50:51] op_sel_hi:[0,1]
	v_cvt_pk_bf16_f32 v50, v68, v69
	v_cvt_pk_bf16_f32 v51, v66, v67
	v_cvt_pk_bf16_f32 v52, v52, v53
	v_cvt_pk_bf16_f32 v53, v54, v55
	s_nop 0
	v_permlane16_swap_b32_e32 v50, v52
	v_permlane16_swap_b32_e32 v51, v53
	global_store_dwordx4 v[70:71], v[50:53], off offset:256 sc1
	s_nop 1
	v_lshl_add_u64 v[50:51], v[134:135], 0, v[0:1]
	v_lshl_add_u64 v[52:53], v[136:137], 0, v[0:1]
	global_load_dwordx4 v[54:57], v[50:51], off
	global_load_dwordx4 v[58:61], v[52:53], off
	v_lshlrev_b32_e32 v0, 7, v174
	v_and_b32_e32 v0, 0xff780, v0
	s_waitcnt vmcnt(0)
	v_pk_mul_f32 v[62:63], v[44:45], v[60:61]
	v_pk_mul_f32 v[64:65], v[42:43], v[58:59]
	v_pk_fma_f32 v[62:63], v[48:49], v[56:57], v[62:63] neg_lo:[0,0,1] neg_hi:[0,0,1]
	v_pk_fma_f32 v[64:65], v[46:47], v[54:55], v[64:65] neg_lo:[0,0,1] neg_hi:[0,0,1]
	v_pk_mul_f32 v[48:49], v[48:49], v[60:61]
	v_pk_mul_f32 v[46:47], v[46:47], v[58:59]
	v_pk_fma_f32 v[44:45], v[44:45], v[56:57], v[48:49]
	v_pk_fma_f32 v[42:43], v[42:43], v[54:55], v[46:47]
	v_pk_mul_f32 v[46:47], v[164:165], v[44:45] op_sel_hi:[0,1]
	v_pk_mul_f32 v[44:45], v[164:165], v[42:43] op_sel_hi:[0,1]
	v_mad_i64_i32 v[42:43], s[68:69], v175, s33, v[122:123]
	v_lshl_add_u64 v[42:43], v[42:43], 0, s[66:67]
	v_pk_mul_f32 v[62:63], v[164:165], v[62:63] op_sel_hi:[0,1]
	v_pk_mul_f32 v[64:65], v[164:165], v[64:65] op_sel_hi:[0,1]
	v_lshl_add_u64 v[42:43], v[42:43], 0, s[36:37]
	v_lshl_add_u64 v[48:49], v[42:43], 0, v[142:143]
	v_cvt_pk_bf16_f32 v42, v64, v65
	v_cvt_pk_bf16_f32 v43, v62, v63
	v_cvt_pk_bf16_f32 v44, v44, v45
	v_cvt_pk_bf16_f32 v45, v46, v47
	s_nop 0
	v_permlane16_swap_b32_e32 v42, v44
	v_permlane16_swap_b32_e32 v43, v45
	v_lshl_add_u64 v[54:55], v[48:49], 0, v[144:145]
	global_store_dwordx4 v[54:55], v[42:45], off sc1
	global_load_dwordx4 v[42:45], v[50:51], off
	global_load_dwordx4 v[46:49], v[52:53], off
	s_waitcnt vmcnt(0)
	v_pk_mul_f32 v[50:51], v[36:37], v[48:49]
	v_pk_mul_f32 v[52:53], v[34:35], v[46:47]
	v_pk_fma_f32 v[50:51], v[40:41], v[44:45], v[50:51] neg_lo:[0,0,1] neg_hi:[0,0,1]
	v_pk_fma_f32 v[52:53], v[38:39], v[42:43], v[52:53] neg_lo:[0,0,1] neg_hi:[0,0,1]
	v_pk_mul_f32 v[40:41], v[40:41], v[48:49]
	v_pk_mul_f32 v[38:39], v[38:39], v[46:47]
	v_pk_fma_f32 v[36:37], v[36:37], v[44:45], v[40:41]
	v_pk_fma_f32 v[34:35], v[34:35], v[42:43], v[38:39]
	v_pk_mul_f32 v[50:51], v[164:165], v[50:51] op_sel_hi:[0,1]
	v_pk_mul_f32 v[52:53], v[164:165], v[52:53] op_sel_hi:[0,1]
	v_pk_mul_f32 v[38:39], v[164:165], v[36:37] op_sel_hi:[0,1]
	v_pk_mul_f32 v[36:37], v[164:165], v[34:35] op_sel_hi:[0,1]
	v_cvt_pk_bf16_f32 v34, v52, v53
	v_cvt_pk_bf16_f32 v35, v50, v51
	v_cvt_pk_bf16_f32 v36, v36, v37
	v_cvt_pk_bf16_f32 v37, v38, v39
	s_nop 0
	v_permlane16_swap_b32_e32 v34, v36
	v_permlane16_swap_b32_e32 v35, v37
	global_store_dwordx4 v[54:55], v[34:37], off offset:256 sc1
	s_nop 1
	v_lshl_add_u64 v[34:35], v[134:135], 0, v[0:1]
	v_lshl_add_u64 v[36:37], v[136:137], 0, v[0:1]
	global_load_dwordx4 v[38:41], v[34:35], off
	global_load_dwordx4 v[42:45], v[36:37], off
	v_lshlrev_b32_e32 v0, 7, v173
	v_and_b32_e32 v0, 0xfff80, v0
	s_waitcnt vmcnt(0)
; __device__ __forceinline__ unsigned pk2(float lo, float hi) { f32x2 v = {lo, hi}; bf16x2_t b = __builtin_convertvector(v, bf16x2_t); return __builtin_bit_cast(unsigned, b); }
; __device__ __forceinline__ void swap16(unsigned& a, unsigned& b) { auto r = __builtin_amdgcn_permlane16_swap(a, b, false, false); a = r[0]; b = r[1]; }
; template <class Epi, class Sched>
; __device__ __forceinline__ void gemm_phase(LAS unsigned char* lds, const Gemm g, const Sched& S, const Epi& E) {
;     ...
;         if (!has_next) break;
; #pragma unroll
;         for (int a = 0; a < 2; ++a)
; #pragma unroll
;             for (int b = 0; b < 2; ++b)
; #pragma unroll
;                 for (int m = 0; m < 4; ++m)
; #pragma unroll
;                     for (int n = 0; n < 2; ++n) acc[a][b][m][n] = (f32x4){0.f, 0.f, 0.f, 0.f};
;         cur = nxt; cA = nA; cB = nB; ++ui;
;     __device__ __forceinline__ void operator()(const f32x4 (&acc)[2][2][4][2], const Unit& u, int wr, int wc, int fr, int fq) const {
;     ...
;         if (u.pn < 8) {
; #pragma unroll
;             for (int ai = 0; ai < 2; ++ai)
; #pragma unroll
;                 for (int m = 0; m < 4; ++m) {
;                     const int row = row0 + ai * HALF + m * 16, pos = row & (SEQ - 1);
; #pragma unroll
;                     for (int bj = 0; bj < 2; ++bj) {
;                         const int g = 4 * bj + wc, hl = g >> 1, d0 = (g & 1) * 16 + 4 * fq;
;                         const f32x4 c = *(const f32x4*)(cosT + pos * 32 + d0), s = *(const f32x4*)(sinT + pos * 32 + d0);
;                         const f32x4 x1 = acc[ai][bj][m][0], x2 = acc[ai][bj][m][1];
;                         const float qs = (u.pn < 4) ? 0.125f * 1.4426950408889634f : 1.0f;
;                         const f32x4 o1 = (x1 * c - x2 * s) * qs, o2 = (x2 * c + x1 * s) * qs;
;                         bf16_t* p = P + (size_t)row * INC + u.pn * BM + hl * 64 + d0;
;                         unsigned a0 = pk2(o1[0], o1[1]), a1 = pk2(o1[2], o1[3]), b0 = pk2(o2[0], o2[1]), b1 = pk2(o2[2], o2[3]);
;                         swap16(a0, b0); swap16(a1, b1);
;                         *(u32x4*)(p + ((fq & 1) ? 28 : 0)) = (u32x4){a0, a1, b0, b1};
;                         asm volatile("" ::: "memory");
;                     }
;                 }
	v_pk_mul_f32 v[46:47], v[28:29], v[44:45]
	v_pk_mul_f32 v[48:49], v[26:27], v[42:43]
	v_pk_fma_f32 v[46:47], v[32:33], v[40:41], v[46:47] neg_lo:[0,0,1] neg_hi:[0,0,1]
	v_pk_fma_f32 v[48:49], v[30:31], v[38:39], v[48:49] neg_lo:[0,0,1] neg_hi:[0,0,1]
	v_pk_mul_f32 v[32:33], v[32:33], v[44:45]
	v_pk_mul_f32 v[30:31], v[30:31], v[42:43]
	v_pk_fma_f32 v[28:29], v[28:29], v[40:41], v[32:33]
	v_pk_fma_f32 v[26:27], v[26:27], v[38:39], v[30:31]
	v_pk_mul_f32 v[30:31], v[164:165], v[28:29] op_sel_hi:[0,1]
	v_pk_mul_f32 v[28:29], v[164:165], v[26:27] op_sel_hi:[0,1]
	v_mad_i64_i32 v[26:27], s[68:69], v174, s33, v[122:123]
	v_lshl_add_u64 v[26:27], v[26:27], 0, s[66:67]
	v_pk_mul_f32 v[46:47], v[164:165], v[46:47] op_sel_hi:[0,1]
	v_pk_mul_f32 v[48:49], v[164:165], v[48:49] op_sel_hi:[0,1]
	v_lshl_add_u64 v[26:27], v[26:27], 0, s[36:37]
	v_lshl_add_u64 v[32:33], v[26:27], 0, v[142:143]
	v_cvt_pk_bf16_f32 v26, v48, v49
	v_cvt_pk_bf16_f32 v27, v46, v47
	v_cvt_pk_bf16_f32 v28, v28, v29
	v_cvt_pk_bf16_f32 v29, v30, v31
	s_nop 0
	v_permlane16_swap_b32_e32 v26, v28
	v_permlane16_swap_b32_e32 v27, v29
	v_lshl_add_u64 v[38:39], v[32:33], 0, v[144:145]
	global_store_dwordx4 v[38:39], v[26:29], off sc1
	global_load_dwordx4 v[26:29], v[34:35], off
	global_load_dwordx4 v[30:33], v[36:37], off
	s_waitcnt vmcnt(0)
	v_pk_mul_f32 v[34:35], v[20:21], v[32:33]
	v_pk_mul_f32 v[36:37], v[18:19], v[30:31]
	v_pk_fma_f32 v[34:35], v[24:25], v[28:29], v[34:35] neg_lo:[0,0,1] neg_hi:[0,0,1]
	v_pk_fma_f32 v[36:37], v[22:23], v[26:27], v[36:37] neg_lo:[0,0,1] neg_hi:[0,0,1]
	v_pk_mul_f32 v[24:25], v[24:25], v[32:33]
	v_pk_mul_f32 v[22:23], v[22:23], v[30:31]
	v_pk_fma_f32 v[20:21], v[20:21], v[28:29], v[24:25]
	v_pk_fma_f32 v[18:19], v[18:19], v[26:27], v[22:23]
	v_pk_mul_f32 v[34:35], v[164:165], v[34:35] op_sel_hi:[0,1]
	v_pk_mul_f32 v[36:37], v[164:165], v[36:37] op_sel_hi:[0,1]
	v_pk_mul_f32 v[22:23], v[164:165], v[20:21] op_sel_hi:[0,1]
	v_pk_mul_f32 v[20:21], v[164:165], v[18:19] op_sel_hi:[0,1]
	v_cvt_pk_bf16_f32 v18, v36, v37
	v_cvt_pk_bf16_f32 v19, v34, v35
	v_cvt_pk_bf16_f32 v20, v20, v21
	v_cvt_pk_bf16_f32 v21, v22, v23
	s_nop 0
	v_permlane16_swap_b32_e32 v18, v20
	v_permlane16_swap_b32_e32 v19, v21
	global_store_dwordx4 v[38:39], v[18:21], off offset:256 sc1
	s_nop 1
	v_lshl_add_u64 v[18:19], v[134:135], 0, v[0:1]
	v_lshl_add_u64 v[20:21], v[136:137], 0, v[0:1]
	global_load_dwordx4 v[22:25], v[18:19], off
	global_load_dwordx4 v[26:29], v[20:21], off
	s_waitcnt vmcnt(0)
	v_pk_mul_f32 v[30:31], v[12:13], v[28:29]
	v_pk_mul_f32 v[32:33], v[10:11], v[26:27]
	v_pk_fma_f32 v[30:31], v[16:17], v[24:25], v[30:31] neg_lo:[0,0,1] neg_hi:[0,0,1]
	v_pk_fma_f32 v[32:33], v[14:15], v[22:23], v[32:33] neg_lo:[0,0,1] neg_hi:[0,0,1]
	v_pk_mul_f32 v[16:17], v[16:17], v[28:29]
	v_pk_mul_f32 v[14:15], v[14:15], v[26:27]
	v_pk_fma_f32 v[12:13], v[12:13], v[24:25], v[16:17]
	v_pk_fma_f32 v[10:11], v[10:11], v[22:23], v[14:15]
	v_pk_mul_f32 v[14:15], v[164:165], v[12:13] op_sel_hi:[0,1]
	v_pk_mul_f32 v[12:13], v[164:165], v[10:11] op_sel_hi:[0,1]
	v_mad_i64_i32 v[10:11], s[68:69], v173, s33, v[122:123]
	v_lshl_add_u64 v[10:11], v[10:11], 0, s[66:67]
	v_pk_mul_f32 v[30:31], v[164:165], v[30:31] op_sel_hi:[0,1]
	v_pk_mul_f32 v[32:33], v[164:165], v[32:33] op_sel_hi:[0,1]
	v_lshl_add_u64 v[10:11], v[10:11], 0, s[36:37]
	v_lshl_add_u64 v[16:17], v[10:11], 0, v[142:143]
	v_cvt_pk_bf16_f32 v10, v32, v33
	v_cvt_pk_bf16_f32 v11, v30, v31
	v_cvt_pk_bf16_f32 v12, v12, v13
	v_cvt_pk_bf16_f32 v13, v14, v15
	s_nop 0
	v_permlane16_swap_b32_e32 v10, v12
	v_permlane16_swap_b32_e32 v11, v13
	v_lshl_add_u64 v[22:23], v[16:17], 0, v[144:145]
	global_store_dwordx4 v[22:23], v[10:13], off sc1
	global_load_dwordx4 v[10:13], v[18:19], off
	global_load_dwordx4 v[14:17], v[20:21], off
	s_waitcnt vmcnt(0)
	v_pk_mul_f32 v[18:19], v[4:5], v[16:17]
	v_pk_mul_f32 v[20:21], v[2:3], v[14:15]
	v_pk_fma_f32 v[18:19], v[8:9], v[12:13], v[18:19] neg_lo:[0,0,1] neg_hi:[0,0,1]
	v_pk_fma_f32 v[20:21], v[6:7], v[10:11], v[20:21] neg_lo:[0,0,1] neg_hi:[0,0,1]
	v_pk_mul_f32 v[8:9], v[8:9], v[16:17]
	v_pk_mul_f32 v[6:7], v[6:7], v[14:15]
	v_pk_fma_f32 v[4:5], v[4:5], v[12:13], v[8:9]
	v_pk_fma_f32 v[2:3], v[2:3], v[10:11], v[6:7]
	v_pk_mul_f32 v[18:19], v[164:165], v[18:19] op_sel_hi:[0,1]
	v_pk_mul_f32 v[20:21], v[164:165], v[20:21] op_sel_hi:[0,1]
	v_pk_mul_f32 v[6:7], v[164:165], v[4:5] op_sel_hi:[0,1]
	v_pk_mul_f32 v[4:5], v[164:165], v[2:3] op_sel_hi:[0,1]
	v_cvt_pk_bf16_f32 v2, v20, v21
	v_cvt_pk_bf16_f32 v3, v18, v19
	v_cvt_pk_bf16_f32 v4, v4, v5
	v_cvt_pk_bf16_f32 v5, v6, v7
	s_nop 0
	v_permlane16_swap_b32_e32 v2, v4
	v_permlane16_swap_b32_e32 v3, v5
	global_store_dwordx4 v[22:23], v[2:5], off offset:256 sc1
	s_andn2_b64 vcc, exec, s[42:43]
	s_mov_b64 s[42:43], -1
	s_cbranch_vccnz .LBB0_152

;     __device__ __forceinline__ void operator()(f32x4 (&acc)[2][2][4][2], const Unit& u, int wr, int wc, int fr, int fq) const {
;     ...
; #pragma unroll
;         for (int ai = 0; ai < 2; ++ai)
; #pragma unroll
;             for (int mp = 0; mp < 2; ++mp) {
;                 f32x4 b[2][2][2];
; #pragma unroll
;                 for (int mm = 0; mm < 2; ++mm) { const size_t off = (size_t)(row0 + ai * HALF + (2 * mp + mm) * 16) * D + col0;
; #pragma unroll
;                     for (int bj = 0; bj < 2; ++bj)
; #pragma unroll
;                         for (int n = 0; n < 2; ++n) b[mm][bj][n] = *(const f32x4*)(base + off + bj * HALF + n * 16); }
; #pragma unroll
;                 for (int mm = 0; mm < 2; ++mm) { const int m = 2 * mp + mm; const int row = row0 + ai * HALF + m * 16; const size_t off = (size_t)row * D + col0;
;                     float sq = 0.f;
; #pragma unroll
;                     for (int bj = 0; bj < 2; ++bj)
; #pragma unroll
;                         for (int n = 0; n < 2; ++n) { const f32x4 v = b[mm][bj][n] + alpha * acc[ai][bj][m][n]; acc[ai][bj][m][n] = v;
;                             if (!FINAL) *(f32x4*)(out + off + bj * HALF + n * 16) = v;
;                             sq += (v.x * v.x + v.y * v.y) + (v.z * v.z + v.w * v.w); }
;                     sq += __shfl_xor(sq, 16); sq += __shfl_xor(sq, 32);
;                     if (fq == 0) __hip_atomic_store((unsigned*)(slots + (size_t)row * 32 + u.pn * 4 + wc), __builtin_bit_cast(unsigned, sq), __ATOMIC_RELAXED, __HIP_MEMORY_SCOPE_AGENT);
;                 }
.LBB0_295:
	v_and_b32_e32 v131, 64, v221
	v_xor_b32_e32 v130, 16, v221
	v_add_u32_e32 v131, 64, v131
	v_cmp_lt_i32_e32 vcc, v130, v131
	v_lshl_add_u32 v182, s92, 8, v222
	v_ashrrev_i32_e32 v183, 31, v182
	v_cndmask_b32_e32 v130, v221, v130, vcc
	v_lshlrev_b32_e32 v225, 2, v130
	v_xor_b32_e32 v130, 32, v221
	v_cmp_lt_i32_e32 vcc, v130, v131
	v_lshlrev_b64 v[202:203], 13, v[182:183]
	v_or_b32_e32 v180, 16, v182
	v_cndmask_b32_e32 v130, v221, v130, vcc
	v_lshlrev_b32_e32 v226, 2, v130
	v_lshl_add_u64 v[130:131], v[168:169], 0, v[202:203]
	global_load_dwordx4 v[186:189], v[130:131], off
	global_load_dwordx4 v[190:193], v[130:131], off offset:64
	global_load_dwordx4 v[194:197], v[130:131], off offset:512
	global_load_dwordx4 v[198:201], v[130:131], off offset:576
	v_ashrrev_i32_e32 v181, 31, v180
	v_lshlrev_b64 v[184:185], 13, v[180:181]
	v_lshl_add_u64 v[130:131], v[168:169], 0, v[184:185]
	global_load_dwordx4 v[142:145], v[130:131], off
	global_load_dwordx4 v[138:141], v[130:131], off offset:64
	global_load_dwordx4 v[134:137], v[130:131], off offset:512
	s_nop 0
	global_load_dwordx4 v[130:133], v[130:131], off offset:576
	s_waitcnt vmcnt(0)
	v_pk_fma_f32 v[4:5], s[64:65], v[4:5], v[188:189]
	v_pk_fma_f32 v[2:3], s[48:49], v[2:3], v[186:187]
	v_mul_f32_e32 v189, v5, v5
	v_mul_f32_e32 v188, v3, v3
	v_fmac_f32_e32 v188, v2, v2
	v_fmac_f32_e32 v189, v4, v4
	v_pk_fma_f32 v[8:9], s[64:65], v[8:9], v[192:193]
	v_pk_fma_f32 v[6:7], s[48:49], v[6:7], v[190:191]
	v_add_f32_e32 v188, v188, v189
	v_mul_f32_e32 v189, v7, v7
	v_mul_f32_e32 v190, v9, v9
	v_fmac_f32_e32 v189, v6, v6
	v_fmac_f32_e32 v190, v8, v8
	v_add_f32_e32 v189, v189, v190
	v_pk_fma_f32 v[12:13], s[64:65], v[12:13], v[196:197]
	v_pk_fma_f32 v[10:11], s[48:49], v[10:11], v[194:195]
	v_lshl_add_u64 v[186:187], v[170:171], 0, v[202:203]
	v_add_f32_e32 v188, v188, v189
	v_mul_f32_e32 v189, v11, v11
	v_mul_f32_e32 v190, v13, v13
	v_pk_fma_f32 v[16:17], s[64:65], v[16:17], v[200:201]
	v_pk_fma_f32 v[14:15], s[48:49], v[14:15], v[198:199]
	global_store_dwordx4 v[186:187], v[2:5], off sc1
	global_store_dwordx4 v[186:187], v[6:9], off offset:64 sc1
	global_store_dwordx4 v[186:187], v[10:13], off offset:512 sc1
	v_fmac_f32_e32 v189, v10, v10
	v_fmac_f32_e32 v190, v12, v12
	global_store_dwordx4 v[186:187], v[14:17], off offset:576 sc1
	v_mul_f32_e32 v186, v15, v15
	v_mul_f32_e32 v187, v17, v17
	v_add_f32_e32 v189, v189, v190
	v_fmac_f32_e32 v186, v14, v14
	v_fmac_f32_e32 v187, v16, v16
	v_add_f32_e32 v188, v188, v189
	v_add_f32_e32 v186, v186, v187
	v_add_f32_e32 v186, v188, v186
	ds_bpermute_b32 v187, v225, v186
	v_lshlrev_b64 v[196:197], 7, v[182:183]
	s_waitcnt lgkmcnt(0)
	v_add_f32_e32 v186, v186, v187
	ds_bpermute_b32 v187, v226, v186
	s_and_saveexec_b64 s[46:47], s[42:43]
	s_cbranch_execz .LBB0_297
	s_waitcnt lgkmcnt(0)
	v_add_f32_e32 v188, v186, v187
	v_lshl_add_u64 v[186:187], s[66:67], 0, v[196:197]
	global_store_dword v[186:187], v188, off sc1
.LBB0_297:
	s_or_b64 exec, exec, s[46:47]
	v_pk_fma_f32 v[20:21], s[64:65], v[20:21], v[144:145]
	v_pk_fma_f32 v[18:19], s[48:49], v[18:19], v[142:143]
	v_pk_fma_f32 v[28:29], s[64:65], v[28:29], v[140:141]
	v_pk_fma_f32 v[26:27], s[48:49], v[26:27], v[138:139]
	v_mul_f32_e32 v142, v19, v19
	v_mul_f32_e32 v143, v21, v21
	v_mul_f32_e32 v138, v27, v27
	v_mul_f32_e32 v139, v29, v29
	v_pk_fma_f32 v[24:25], s[64:65], v[24:25], v[136:137]
	v_pk_fma_f32 v[22:23], s[48:49], v[22:23], v[134:135]
	v_fmac_f32_e32 v142, v18, v18
	v_fmac_f32_e32 v143, v20, v20
	v_fmac_f32_e32 v138, v26, v26
	v_fmac_f32_e32 v139, v28, v28
	v_mul_f32_e32 v134, v23, v23
	v_mul_f32_e32 v135, v25, v25
	v_pk_fma_f32 v[32:33], s[64:65], v[32:33], v[132:133]
	v_pk_fma_f32 v[30:31], s[48:49], v[30:31], v[130:131]
	v_add_f32_e32 v142, v142, v143
	v_add_f32_e32 v138, v138, v139
	v_fmac_f32_e32 v134, v22, v22
	v_fmac_f32_e32 v135, v24, v24
	v_mul_f32_e32 v130, v31, v31
	v_mul_f32_e32 v131, v33, v33
	v_add_f32_e32 v138, v142, v138
	v_add_f32_e32 v134, v134, v135
	v_fmac_f32_e32 v130, v30, v30
	v_fmac_f32_e32 v131, v32, v32
	v_add_f32_e32 v134, v138, v134
	v_add_f32_e32 v130, v130, v131
	v_add_f32_e32 v130, v134, v130
	ds_bpermute_b32 v131, v225, v130
	v_lshl_add_u64 v[132:133], v[170:171], 0, v[184:185]
	v_lshlrev_b64 v[198:199], 7, v[180:181]
	global_store_dwordx4 v[132:133], v[18:21], off sc1
	global_store_dwordx4 v[132:133], v[26:29], off offset:64 sc1
	global_store_dwordx4 v[132:133], v[22:25], off offset:512 sc1
	global_store_dwordx4 v[132:133], v[30:33], off offset:576 sc1
	s_waitcnt lgkmcnt(0)
	v_add_f32_e32 v130, v130, v131
	ds_bpermute_b32 v131, v226, v130
	s_and_saveexec_b64 s[46:47], s[42:43]
	s_cbranch_execz .LBB0_299
	s_waitcnt lgkmcnt(0)
	v_add_f32_e32 v132, v130, v131
	v_lshl_add_u64 v[130:131], s[66:67], 0, v[198:199]
	global_store_dword v[130:131], v132, off sc1
;     __device__ __forceinline__ void operator()(f32x4 (&acc)[2][2][4][2], const Unit& u, int wr, int wc, int fr, int fq) const {
;     ...
; #pragma unroll
;         for (int ai = 0; ai < 2; ++ai)
; #pragma unroll
;             for (int mp = 0; mp < 2; ++mp) {
;                 f32x4 b[2][2][2];
; #pragma unroll
;                 for (int mm = 0; mm < 2; ++mm) { const size_t off = (size_t)(row0 + ai * HALF + (2 * mp + mm) * 16) * D + col0;
; #pragma unroll
;                     for (int bj = 0; bj < 2; ++bj)
; #pragma unroll
;                         for (int n = 0; n < 2; ++n) b[mm][bj][n] = *(const f32x4*)(base + off + bj * HALF + n * 16); }
; #pragma unroll
;                 for (int mm = 0; mm < 2; ++mm) { const int m = 2 * mp + mm; const int row = row0 + ai * HALF + m * 16; const size_t off = (size_t)row * D + col0;
;                     float sq = 0.f;
; #pragma unroll
;                     for (int bj = 0; bj < 2; ++bj)
; #pragma unroll
;                         for (int n = 0; n < 2; ++n) { const f32x4 v = b[mm][bj][n] + alpha * acc[ai][bj][m][n]; acc[ai][bj][m][n] = v;
;                             if (!FINAL) *(f32x4*)(out + off + bj * HALF + n * 16) = v;
;                             sq += (v.x * v.x + v.y * v.y) + (v.z * v.z + v.w * v.w); }
;                     sq += __shfl_xor(sq, 16); sq += __shfl_xor(sq, 32);
;                     if (fq == 0) __hip_atomic_store((unsigned*)(slots + (size_t)row * 32 + u.pn * 4 + wc), __builtin_bit_cast(unsigned, sq), __ATOMIC_RELAXED, __HIP_MEMORY_SCOPE_AGENT);
;                 }
.LBB0_299:
	s_or_b64 exec, exec, s[46:47]
	v_or_b32_e32 v186, 32, v182
	v_ashrrev_i32_e32 v187, 31, v186
	v_lshlrev_b64 v[194:195], 13, v[186:187]
	s_waitcnt lgkmcnt(0)
	v_lshl_add_u64 v[130:131], v[168:169], 0, v[194:195]
	global_load_dwordx4 v[190:193], v[130:131], off
	global_load_dwordx4 v[200:203], v[130:131], off offset:64
	global_load_dwordx4 v[204:207], v[130:131], off offset:512
	global_load_dwordx4 v[208:211], v[130:131], off offset:576
	v_or_b32_e32 v184, 48, v182
	v_ashrrev_i32_e32 v185, 31, v184
	v_lshlrev_b64 v[188:189], 13, v[184:185]
	v_lshl_add_u64 v[130:131], v[168:169], 0, v[188:189]
	global_load_dwordx4 v[142:145], v[130:131], off
	global_load_dwordx4 v[138:141], v[130:131], off offset:64
	global_load_dwordx4 v[134:137], v[130:131], off offset:512
	s_nop 0
	global_load_dwordx4 v[130:133], v[130:131], off offset:576
	s_waitcnt vmcnt(7)
	v_pk_fma_f32 v[36:37], s[64:65], v[36:37], v[192:193]
	v_pk_fma_f32 v[34:35], s[48:49], v[34:35], v[190:191]
	s_waitcnt vmcnt(6)
	v_pk_fma_f32 v[44:45], s[64:65], v[44:45], v[202:203]
	v_pk_fma_f32 v[42:43], s[48:49], v[42:43], v[200:201]
	s_waitcnt vmcnt(5)
	v_pk_fma_f32 v[40:41], s[64:65], v[40:41], v[206:207]
	v_pk_fma_f32 v[38:39], s[48:49], v[38:39], v[204:205]
	v_mul_f32_e32 v190, v35, v35
	v_mul_f32_e32 v191, v37, v37
	v_mul_f32_e32 v192, v43, v43
	v_mul_f32_e32 v193, v45, v45
	s_waitcnt vmcnt(4)
	v_pk_fma_f32 v[48:49], s[64:65], v[48:49], v[210:211]
	v_pk_fma_f32 v[46:47], s[48:49], v[46:47], v[208:209]
	v_mul_f32_e32 v200, v39, v39
	v_mul_f32_e32 v201, v41, v41
	v_fmac_f32_e32 v190, v34, v34
	v_fmac_f32_e32 v191, v36, v36
	v_fmac_f32_e32 v192, v42, v42
	v_fmac_f32_e32 v193, v44, v44
	v_mul_f32_e32 v202, v47, v47
	v_mul_f32_e32 v203, v49, v49
	v_fmac_f32_e32 v200, v38, v38
	v_fmac_f32_e32 v201, v40, v40
	v_add_f32_e32 v190, v190, v191
	v_add_f32_e32 v191, v192, v193
	v_fmac_f32_e32 v202, v46, v46
	v_fmac_f32_e32 v203, v48, v48
	v_add_f32_e32 v192, v200, v201
	v_add_f32_e32 v190, v190, v191
	v_add_f32_e32 v190, v190, v192
	v_add_f32_e32 v191, v202, v203
	v_add_f32_e32 v190, v190, v191
	ds_bpermute_b32 v191, v225, v190
	v_lshl_add_u64 v[192:193], v[170:171], 0, v[194:195]
	v_lshlrev_b64 v[200:201], 7, v[186:187]
	global_store_dwordx4 v[192:193], v[34:37], off sc1
	global_store_dwordx4 v[192:193], v[42:45], off offset:64 sc1
	global_store_dwordx4 v[192:193], v[38:41], off offset:512 sc1
	global_store_dwordx4 v[192:193], v[46:49], off offset:576 sc1
	s_waitcnt lgkmcnt(0)
	v_add_f32_e32 v190, v190, v191
	ds_bpermute_b32 v191, v226, v190
	s_and_saveexec_b64 s[46:47], s[42:43]
	s_cbranch_execz .LBB0_301
	s_waitcnt lgkmcnt(0)
	v_add_f32_e32 v192, v190, v191
	v_lshl_add_u64 v[190:191], s[66:67], 0, v[200:201]
	global_store_dword v[190:191], v192, off sc1
.LBB0_301:
	s_or_b64 exec, exec, s[46:47]
	s_waitcnt vmcnt(7)
	v_pk_fma_f32 v[52:53], s[64:65], v[52:53], v[144:145]
	v_pk_fma_f32 v[50:51], s[48:49], v[50:51], v[142:143]
	s_waitcnt vmcnt(6)
	v_pk_fma_f32 v[60:61], s[64:65], v[60:61], v[140:141]
	v_pk_fma_f32 v[58:59], s[48:49], v[58:59], v[138:139]
	v_mul_f32_e32 v142, v51, v51
	v_mul_f32_e32 v143, v53, v53
	v_mul_f32_e32 v138, v59, v59
	v_mul_f32_e32 v139, v61, v61
	s_waitcnt vmcnt(5)
	v_pk_fma_f32 v[56:57], s[64:65], v[56:57], v[136:137]
	v_pk_fma_f32 v[54:55], s[48:49], v[54:55], v[134:135]
	v_fmac_f32_e32 v142, v50, v50
	v_fmac_f32_e32 v143, v52, v52
	v_fmac_f32_e32 v138, v58, v58
	v_fmac_f32_e32 v139, v60, v60
	v_mul_f32_e32 v134, v55, v55
	v_mul_f32_e32 v135, v57, v57
	s_waitcnt vmcnt(4)
	v_pk_fma_f32 v[64:65], s[64:65], v[64:65], v[132:133]
	v_pk_fma_f32 v[62:63], s[48:49], v[62:63], v[130:131]
	v_add_f32_e32 v142, v142, v143
	v_add_f32_e32 v138, v138, v139
	v_fmac_f32_e32 v134, v54, v54
	v_fmac_f32_e32 v135, v56, v56
	v_mul_f32_e32 v130, v63, v63
	v_mul_f32_e32 v131, v65, v65
	v_add_f32_e32 v138, v142, v138
	v_add_f32_e32 v134, v134, v135
	v_fmac_f32_e32 v130, v62, v62
	v_fmac_f32_e32 v131, v64, v64
	v_add_f32_e32 v134, v138, v134
	v_add_f32_e32 v130, v130, v131
	v_add_f32_e32 v130, v134, v130
	ds_bpermute_b32 v131, v225, v130
	v_lshl_add_u64 v[132:133], v[170:171], 0, v[188:189]
	v_lshlrev_b64 v[202:203], 7, v[184:185]
	global_store_dwordx4 v[132:133], v[50:53], off sc1
	global_store_dwordx4 v[132:133], v[58:61], off offset:64 sc1
	global_store_dwordx4 v[132:133], v[54:57], off offset:512 sc1
	global_store_dwordx4 v[132:133], v[62:65], off offset:576 sc1
	s_waitcnt lgkmcnt(0)
	v_add_f32_e32 v130, v130, v131
	ds_bpermute_b32 v131, v226, v130
	s_and_saveexec_b64 s[46:47], s[42:43]
	s_cbranch_execz .LBB0_303
	s_waitcnt lgkmcnt(0)
	v_add_f32_e32 v132, v130, v131
	v_lshl_add_u64 v[130:131], s[66:67], 0, v[202:203]
	global_store_dword v[130:131], v132, off sc1
;     __device__ __forceinline__ void operator()(f32x4 (&acc)[2][2][4][2], const Unit& u, int wr, int wc, int fr, int fq) const {
;     ...
; #pragma unroll
;         for (int ai = 0; ai < 2; ++ai)
; #pragma unroll
;             for (int mp = 0; mp < 2; ++mp) {
;                 f32x4 b[2][2][2];
; #pragma unroll
;                 for (int mm = 0; mm < 2; ++mm) { const size_t off = (size_t)(row0 + ai * HALF + (2 * mp + mm) * 16) * D + col0;
; #pragma unroll
;                     for (int bj = 0; bj < 2; ++bj)
; #pragma unroll
;                         for (int n = 0; n < 2; ++n) b[mm][bj][n] = *(const f32x4*)(base + off + bj * HALF + n * 16); }
; #pragma unroll
;                 for (int mm = 0; mm < 2; ++mm) { const int m = 2 * mp + mm; const int row = row0 + ai * HALF + m * 16; const size_t off = (size_t)row * D + col0;
;                     float sq = 0.f;
; #pragma unroll
;                     for (int bj = 0; bj < 2; ++bj)
; #pragma unroll
;                         for (int n = 0; n < 2; ++n) { const f32x4 v = b[mm][bj][n] + alpha * acc[ai][bj][m][n]; acc[ai][bj][m][n] = v;
;                             if (!FINAL) *(f32x4*)(out + off + bj * HALF + n * 16) = v;
;                             sq += (v.x * v.x + v.y * v.y) + (v.z * v.z + v.w * v.w); }
;                     sq += __shfl_xor(sq, 16); sq += __shfl_xor(sq, 32);
;                     if (fq == 0) __hip_atomic_store((unsigned*)(slots + (size_t)row * 32 + u.pn * 4 + wc), __builtin_bit_cast(unsigned, sq), __ATOMIC_RELAXED, __HIP_MEMORY_SCOPE_AGENT);
;                 }
.LBB0_303:
	s_or_b64 exec, exec, s[46:47]
	v_add_u32_e32 v190, 0x80, v182
	v_ashrrev_i32_e32 v191, 31, v190
	v_lshlrev_b64 v[194:195], 13, v[190:191]
	s_waitcnt lgkmcnt(0)
	v_lshl_add_u64 v[130:131], v[168:169], 0, v[194:195]
	global_load_dwordx4 v[204:207], v[130:131], off
	global_load_dwordx4 v[208:211], v[130:131], off offset:64
	global_load_dwordx4 v[228:231], v[130:131], off offset:512
	global_load_dwordx4 v[232:235], v[130:131], off offset:576
	v_add_u32_e32 v188, 0x90, v182
	v_ashrrev_i32_e32 v189, 31, v188
	v_lshlrev_b64 v[192:193], 13, v[188:189]
	v_lshl_add_u64 v[130:131], v[168:169], 0, v[192:193]
	global_load_dwordx4 v[142:145], v[130:131], off
	global_load_dwordx4 v[138:141], v[130:131], off offset:64
	global_load_dwordx4 v[134:137], v[130:131], off offset:512
	s_nop 0
	global_load_dwordx4 v[130:133], v[130:131], off offset:576
	s_waitcnt vmcnt(7)
	v_pk_fma_f32 v[68:69], s[64:65], v[68:69], v[206:207]
	v_pk_fma_f32 v[66:67], s[48:49], v[66:67], v[204:205]
	s_waitcnt vmcnt(6)
	v_pk_fma_f32 v[76:77], s[64:65], v[76:77], v[210:211]
	v_pk_fma_f32 v[74:75], s[48:49], v[74:75], v[208:209]
	s_waitcnt vmcnt(5)
	v_pk_fma_f32 v[72:73], s[64:65], v[72:73], v[230:231]
	v_pk_fma_f32 v[70:71], s[48:49], v[70:71], v[228:229]
	v_mul_f32_e32 v204, v67, v67
	v_mul_f32_e32 v205, v69, v69
	v_mul_f32_e32 v206, v75, v75
	v_mul_f32_e32 v207, v77, v77
	s_waitcnt vmcnt(4)
	v_pk_fma_f32 v[80:81], s[64:65], v[80:81], v[234:235]
	v_pk_fma_f32 v[78:79], s[48:49], v[78:79], v[232:233]
	v_mul_f32_e32 v208, v71, v71
	v_mul_f32_e32 v209, v73, v73
	v_fmac_f32_e32 v204, v66, v66
	v_fmac_f32_e32 v205, v68, v68
	v_fmac_f32_e32 v206, v74, v74
	v_fmac_f32_e32 v207, v76, v76
	v_mul_f32_e32 v210, v79, v79
	v_mul_f32_e32 v211, v81, v81
	v_fmac_f32_e32 v208, v70, v70
	v_fmac_f32_e32 v209, v72, v72
	v_add_f32_e32 v204, v204, v205
	v_add_f32_e32 v205, v206, v207
	v_fmac_f32_e32 v210, v78, v78
	v_fmac_f32_e32 v211, v80, v80
	v_add_f32_e32 v206, v208, v209
	v_add_f32_e32 v204, v204, v205
	v_add_f32_e32 v204, v204, v206
	v_add_f32_e32 v205, v210, v211
	v_add_f32_e32 v206, v204, v205
	ds_bpermute_b32 v207, v225, v206
	v_lshl_add_u64 v[204:205], v[170:171], 0, v[194:195]
	global_store_dwordx4 v[204:205], v[66:69], off sc1
	global_store_dwordx4 v[204:205], v[74:77], off offset:64 sc1
	global_store_dwordx4 v[204:205], v[70:73], off offset:512 sc1
	global_store_dwordx4 v[204:205], v[78:81], off offset:576 sc1
	v_lshlrev_b64 v[204:205], 7, v[190:191]
	s_waitcnt lgkmcnt(0)
	v_add_f32_e32 v194, v206, v207
	ds_bpermute_b32 v195, v226, v194
	s_and_saveexec_b64 s[46:47], s[42:43]
	s_cbranch_execz .LBB0_305
	s_waitcnt lgkmcnt(0)
	v_add_f32_e32 v206, v194, v195
	v_lshl_add_u64 v[194:195], s[66:67], 0, v[204:205]
	global_store_dword v[194:195], v206, off sc1
.LBB0_305:
	s_or_b64 exec, exec, s[46:47]
	s_waitcnt vmcnt(7)
	v_pk_fma_f32 v[84:85], s[64:65], v[84:85], v[144:145]
	v_pk_fma_f32 v[82:83], s[48:49], v[82:83], v[142:143]
	s_waitcnt vmcnt(6)
	v_pk_fma_f32 v[92:93], s[64:65], v[92:93], v[140:141]
	v_pk_fma_f32 v[90:91], s[48:49], v[90:91], v[138:139]
	v_mul_f32_e32 v142, v83, v83
	v_mul_f32_e32 v143, v85, v85
	v_mul_f32_e32 v138, v91, v91
	v_mul_f32_e32 v139, v93, v93
	s_waitcnt vmcnt(5)
	v_pk_fma_f32 v[88:89], s[64:65], v[88:89], v[136:137]
	v_pk_fma_f32 v[86:87], s[48:49], v[86:87], v[134:135]
	v_fmac_f32_e32 v142, v82, v82
	v_fmac_f32_e32 v143, v84, v84
	v_fmac_f32_e32 v138, v90, v90
	v_fmac_f32_e32 v139, v92, v92
	v_mul_f32_e32 v134, v87, v87
	v_mul_f32_e32 v135, v89, v89
	s_waitcnt vmcnt(4)
	v_pk_fma_f32 v[96:97], s[64:65], v[96:97], v[132:133]
	v_pk_fma_f32 v[94:95], s[48:49], v[94:95], v[130:131]
	v_add_f32_e32 v142, v142, v143
	v_add_f32_e32 v138, v138, v139
	v_fmac_f32_e32 v134, v86, v86
	v_fmac_f32_e32 v135, v88, v88
	v_mul_f32_e32 v130, v95, v95
	v_mul_f32_e32 v131, v97, v97
	v_add_f32_e32 v138, v142, v138
	v_add_f32_e32 v134, v134, v135
	v_fmac_f32_e32 v130, v94, v94
	v_fmac_f32_e32 v131, v96, v96
	v_add_f32_e32 v134, v138, v134
	v_add_f32_e32 v130, v130, v131
	v_add_f32_e32 v130, v134, v130
	ds_bpermute_b32 v131, v225, v130
	v_lshl_add_u64 v[132:133], v[170:171], 0, v[192:193]
	v_lshlrev_b64 v[206:207], 7, v[188:189]
	global_store_dwordx4 v[132:133], v[82:85], off sc1
	global_store_dwordx4 v[132:133], v[90:93], off offset:64 sc1
	global_store_dwordx4 v[132:133], v[86:89], off offset:512 sc1
	global_store_dwordx4 v[132:133], v[94:97], off offset:576 sc1
	s_waitcnt lgkmcnt(0)
	v_add_f32_e32 v130, v130, v131
	ds_bpermute_b32 v131, v226, v130
	s_and_saveexec_b64 s[46:47], s[42:43]
	s_cbranch_execz .LBB0_307
	s_waitcnt lgkmcnt(0)
	v_add_f32_e32 v132, v130, v131
	v_lshl_add_u64 v[130:131], s[66:67], 0, v[206:207]
	global_store_dword v[130:131], v132, off sc1
;     __device__ __forceinline__ void operator()(f32x4 (&acc)[2][2][4][2], const Unit& u, int wr, int wc, int fr, int fq) const {
;     ...
; #pragma unroll
;         for (int ai = 0; ai < 2; ++ai)
; #pragma unroll
;             for (int mp = 0; mp < 2; ++mp) {
;                 f32x4 b[2][2][2];
; #pragma unroll
;                 for (int mm = 0; mm < 2; ++mm) { const size_t off = (size_t)(row0 + ai * HALF + (2 * mp + mm) * 16) * D + col0;
; #pragma unroll
;                     for (int bj = 0; bj < 2; ++bj)
; #pragma unroll
;                         for (int n = 0; n < 2; ++n) b[mm][bj][n] = *(const f32x4*)(base + off + bj * HALF + n * 16); }
; #pragma unroll
;                 for (int mm = 0; mm < 2; ++mm) { const int m = 2 * mp + mm; const int row = row0 + ai * HALF + m * 16; const size_t off = (size_t)row * D + col0;
;                     float sq = 0.f;
; #pragma unroll
;                     for (int bj = 0; bj < 2; ++bj)
; #pragma unroll
;                         for (int n = 0; n < 2; ++n) { const f32x4 v = b[mm][bj][n] + alpha * acc[ai][bj][m][n]; acc[ai][bj][m][n] = v;
;                             if (!FINAL) *(f32x4*)(out + off + bj * HALF + n * 16) = v;
;                             sq += (v.x * v.x + v.y * v.y) + (v.z * v.z + v.w * v.w); }
;                     sq += __shfl_xor(sq, 16); sq += __shfl_xor(sq, 32);
;                     if (fq == 0) __hip_atomic_store((unsigned*)(slots + (size_t)row * 32 + u.pn * 4 + wc), __builtin_bit_cast(unsigned, sq), __ATOMIC_RELAXED, __HIP_MEMORY_SCOPE_AGENT);
;                 }
.LBB0_307:
	s_or_b64 exec, exec, s[46:47]
	v_add_u32_e32 v194, 0xa0, v182
	v_ashrrev_i32_e32 v195, 31, v194
	v_lshlrev_b64 v[208:209], 13, v[194:195]
	s_waitcnt lgkmcnt(0)
	v_lshl_add_u64 v[130:131], v[168:169], 0, v[208:209]
	global_load_dwordx4 v[228:231], v[130:131], off
	global_load_dwordx4 v[232:235], v[130:131], off offset:64
	global_load_dwordx4 v[236:239], v[130:131], off offset:512
	global_load_dwordx4 v[240:243], v[130:131], off offset:576
	v_add_u32_e32 v192, 0xb0, v182
	v_ashrrev_i32_e32 v193, 31, v192
	v_lshlrev_b64 v[210:211], 13, v[192:193]
	v_lshl_add_u64 v[130:131], v[168:169], 0, v[210:211]
	global_load_dwordx4 v[142:145], v[130:131], off
	global_load_dwordx4 v[138:141], v[130:131], off offset:64
	global_load_dwordx4 v[134:137], v[130:131], off offset:512
	s_nop 0
	global_load_dwordx4 v[130:133], v[130:131], off offset:576
	v_lshl_add_u64 v[208:209], v[170:171], 0, v[208:209]
	s_waitcnt vmcnt(7)
	v_pk_fma_f32 v[100:101], s[64:65], v[100:101], v[230:231]
	v_pk_fma_f32 v[98:99], s[48:49], v[98:99], v[228:229]
	s_waitcnt vmcnt(6)
	v_pk_fma_f32 v[108:109], s[64:65], v[108:109], v[234:235]
	v_pk_fma_f32 v[106:107], s[48:49], v[106:107], v[232:233]
	s_waitcnt vmcnt(5)
	v_pk_fma_f32 v[104:105], s[64:65], v[104:105], v[238:239]
	v_pk_fma_f32 v[102:103], s[48:49], v[102:103], v[236:237]
	v_mul_f32_e32 v216, v99, v99
	v_mul_f32_e32 v217, v101, v101
	v_mul_f32_e32 v227, v107, v107
	v_mul_f32_e32 v228, v109, v109
	s_waitcnt vmcnt(4)
	v_pk_fma_f32 v[112:113], s[64:65], v[112:113], v[242:243]
	v_pk_fma_f32 v[110:111], s[48:49], v[110:111], v[240:241]
	v_mul_f32_e32 v229, v103, v103
	v_mul_f32_e32 v230, v105, v105
	v_fmac_f32_e32 v216, v98, v98
	v_fmac_f32_e32 v217, v100, v100
	v_fmac_f32_e32 v227, v106, v106
	v_fmac_f32_e32 v228, v108, v108
	v_mul_f32_e32 v231, v111, v111
	v_mul_f32_e32 v232, v113, v113
	v_fmac_f32_e32 v229, v102, v102
	v_fmac_f32_e32 v230, v104, v104
	v_add_f32_e32 v216, v216, v217
	v_add_f32_e32 v217, v227, v228
	v_fmac_f32_e32 v231, v110, v110
	v_fmac_f32_e32 v232, v112, v112
	v_add_f32_e32 v227, v229, v230
	v_add_f32_e32 v216, v216, v217
	v_add_f32_e32 v216, v216, v227
	v_add_f32_e32 v217, v231, v232
	v_add_f32_e32 v216, v216, v217
	ds_bpermute_b32 v217, v225, v216
	global_store_dwordx4 v[208:209], v[98:101], off sc1
	global_store_dwordx4 v[208:209], v[106:109], off offset:64 sc1
	global_store_dwordx4 v[208:209], v[102:105], off offset:512 sc1
	global_store_dwordx4 v[208:209], v[110:113], off offset:576 sc1
	v_lshlrev_b64 v[208:209], 7, v[194:195]
	s_waitcnt lgkmcnt(0)
	v_add_f32_e32 v227, v216, v217
	ds_bpermute_b32 v228, v226, v227
	s_and_saveexec_b64 s[46:47], s[42:43]
	s_cbranch_execz .LBB0_309
	s_waitcnt lgkmcnt(0)
	v_add_f32_e32 v227, v227, v228
	v_lshl_add_u64 v[216:217], s[66:67], 0, v[208:209]
	global_store_dword v[216:217], v227, off sc1
.LBB0_309:
	s_or_b64 exec, exec, s[46:47]
	s_waitcnt vmcnt(7)
	v_pk_fma_f32 v[116:117], s[64:65], v[116:117], v[144:145]
	v_pk_fma_f32 v[114:115], s[48:49], v[114:115], v[142:143]
	s_waitcnt vmcnt(6)
	v_pk_fma_f32 v[124:125], s[64:65], v[124:125], v[140:141]
	v_pk_fma_f32 v[122:123], s[48:49], v[122:123], v[138:139]
	v_mul_f32_e32 v142, v115, v115
	v_mul_f32_e32 v143, v117, v117
	v_mul_f32_e32 v138, v123, v123
	v_mul_f32_e32 v139, v125, v125
	s_waitcnt vmcnt(5)
	v_pk_fma_f32 v[120:121], s[64:65], v[120:121], v[136:137]
	v_pk_fma_f32 v[118:119], s[48:49], v[118:119], v[134:135]
	v_fmac_f32_e32 v142, v114, v114
	v_fmac_f32_e32 v143, v116, v116
	v_fmac_f32_e32 v138, v122, v122
	v_fmac_f32_e32 v139, v124, v124
	v_mul_f32_e32 v134, v119, v119
	v_mul_f32_e32 v135, v121, v121
	s_waitcnt vmcnt(4)
	v_pk_fma_f32 v[128:129], s[64:65], v[128:129], v[132:133]
	v_pk_fma_f32 v[126:127], s[48:49], v[126:127], v[130:131]
	v_add_f32_e32 v142, v142, v143
	v_add_f32_e32 v138, v138, v139
	v_fmac_f32_e32 v134, v118, v118
	v_fmac_f32_e32 v135, v120, v120
	v_mul_f32_e32 v130, v127, v127
	v_mul_f32_e32 v131, v129, v129
	v_add_f32_e32 v138, v142, v138
	v_add_f32_e32 v134, v134, v135
	v_fmac_f32_e32 v130, v126, v126
	v_fmac_f32_e32 v131, v128, v128
	v_add_f32_e32 v134, v138, v134
	v_add_f32_e32 v130, v130, v131
	v_add_f32_e32 v130, v134, v130
	ds_bpermute_b32 v131, v225, v130
	v_lshl_add_u64 v[132:133], v[170:171], 0, v[210:211]
	v_lshlrev_b64 v[210:211], 7, v[192:193]
	global_store_dwordx4 v[132:133], v[114:117], off sc1
	global_store_dwordx4 v[132:133], v[122:125], off offset:64 sc1
	global_store_dwordx4 v[132:133], v[118:121], off offset:512 sc1
	global_store_dwordx4 v[132:133], v[126:129], off offset:576 sc1
	s_waitcnt lgkmcnt(0)
	v_add_f32_e32 v130, v130, v131
	ds_bpermute_b32 v131, v226, v130
	s_and_saveexec_b64 s[46:47], s[42:43]
	s_cbranch_execz .LBB0_311
	s_waitcnt lgkmcnt(0)
	v_add_f32_e32 v132, v130, v131
	v_lshl_add_u64 v[130:131], s[66:67], 0, v[210:211]
	global_store_dword v[130:131], v132, off sc1

;     __device__ __forceinline__ void operator()(f32x4 (&acc)[2][2][4][2], const Unit& u, int wr, int wc, int fr, int fq) const {
;     ...
;         asm volatile("s_waitcnt vmcnt(0) lgkmcnt(0)" ::: "memory"); __builtin_amdgcn_s_barrier(); asm volatile("" ::: "memory");
;         float rs[2][4];
; #pragma unroll
;         for (int ai = 0; ai < 2; ++ai) {
;             f32x4 pa[4], pb[4];
; #pragma unroll
;             for (int m = 0; m < 4; ++m) { const float* sp4 = slots + (size_t)(row0 + ai * HALF + m * 16) * 32 + fq * 8;
;                 asm volatile("global_load_dwordx4 %0, %1, off sc0 sc1" : "=v"(pa[m]) : "v"(sp4) : "memory");
;                 asm volatile("global_load_dwordx4 %0, %1, off offset:16 sc0 sc1" : "=v"(pb[m]) : "v"(sp4) : "memory"); }
;             asm volatile("s_waitcnt vmcnt(0)" : "+v"(pa[0]), "+v"(pa[1]), "+v"(pa[2]), "+v"(pa[3]), "+v"(pb[0]), "+v"(pb[1]), "+v"(pb[2]), "+v"(pb[3]) :: "memory");
; #pragma unroll
;             for (int m = 0; m < 4; ++m) {
;                 float t = ((pa[m].x + pa[m].y) + (pa[m].z + pa[m].w)) + ((pb[m].x + pb[m].y) + (pb[m].z + pb[m].w));
;                 t += __shfl_xor(t, 16); t += __shfl_xor(t, 32);
;                 rs[ai][m] = 1.0f / sqrtf(t * (1.0f / D) + NORM_EPS);
.LBB0_328:
	s_waitcnt vmcnt(0) lgkmcnt(0)
	s_barrier
	s_waitcnt lgkmcnt(0)
	v_lshl_add_u64 v[130:131], v[166:167], 0, v[196:197]
	global_load_dwordx4 v[228:231], v[130:131], off sc0 sc1
	global_load_dwordx4 v[232:235], v[130:131], off offset:16 sc0 sc1
	v_lshl_add_u64 v[130:131], v[166:167], 0, v[198:199]
	global_load_dwordx4 v[236:239], v[130:131], off sc0 sc1
	global_load_dwordx4 v[240:243], v[130:131], off offset:16 sc0 sc1
	v_lshl_add_u64 v[130:131], v[166:167], 0, v[200:201]
	global_load_dwordx4 v[142:145], v[130:131], off sc0 sc1
	global_load_dwordx4 v[138:141], v[130:131], off offset:16 sc0 sc1
	v_lshl_add_u64 v[130:131], v[166:167], 0, v[202:203]
	global_load_dwordx4 v[134:137], v[130:131], off sc0 sc1
	global_load_dwordx4 v[130:133], v[130:131], off offset:16 sc0 sc1
	v_lshlrev_b64 v[182:183], 12, v[182:183]
	s_waitcnt vmcnt(0)
	s_mov_b64 s[70:71], -1
	v_mov_b32_e32 v196, v228
	v_mov_b32_e32 v197, v232
	v_mov_b32_e32 v232, v229
	v_mov_b32_e32 v198, v230
	v_mov_b32_e32 v199, v234
	v_mov_b32_e32 v234, v231
	v_pk_add_f32 v[196:197], v[196:197], v[232:233]
	v_pk_add_f32 v[198:199], v[198:199], v[234:235]
	s_nop 0
	v_pk_add_f32 v[196:197], v[196:197], v[198:199]
	s_nop 0
	v_add_f32_e32 v196, v196, v197
	ds_bpermute_b32 v197, v225, v196
	s_waitcnt lgkmcnt(0)
	v_add_f32_e32 v196, v196, v197
	ds_bpermute_b32 v197, v226, v196
	s_waitcnt lgkmcnt(0)
	v_add_f32_e32 v196, v196, v197
	v_fmamk_f32 v196, v196, 0x3a000000, v213
	v_cmp_gt_f32_e32 vcc, s98, v196
	v_mul_f32_e32 v197, 0x4f800000, v196
	s_nop 0
	v_cndmask_b32_e32 v196, v196, v197, vcc
	v_sqrt_f32_e32 v197, v196
	s_nop 0
	v_add_u32_e32 v198, -1, v197
	v_fma_f32 v199, -v198, v197, v196
	v_cmp_ge_f32_e64 s[46:47], 0, v199
	v_add_u32_e32 v199, 1, v197
	s_nop 0
	v_cndmask_b32_e64 v198, v197, v198, s[46:47]
	v_fma_f32 v197, -v199, v197, v196
	v_cmp_lt_f32_e64 s[46:47], 0, v197
	s_nop 1
	v_cndmask_b32_e64 v197, v198, v199, s[46:47]
	v_mul_f32_e32 v198, 0x37800000, v197
	v_cndmask_b32_e32 v197, v197, v198, vcc
	v_cmp_class_f32_e32 vcc, v196, v214
	s_nop 1
	v_cndmask_b32_e32 v196, v197, v196, vcc
	v_div_scale_f32 v197, s[46:47], v196, v196, 1.0
	v_rcp_f32_e32 v198, v197
	s_nop 0
	v_fma_f32 v199, -v197, v198, 1.0
	v_fmac_f32_e32 v198, v199, v198
	v_div_scale_f32 v199, vcc, 1.0, v196, 1.0
	v_mul_f32_e32 v200, v199, v198
	v_fma_f32 v201, -v197, v200, v199
	v_fmac_f32_e32 v200, v201, v198
	v_fma_f32 v197, -v197, v200, v199
	v_div_fmas_f32 v197, v197, v198, v200
	v_mov_b32_e32 v198, v236
	v_mov_b32_e32 v199, v240
	v_mov_b32_e32 v240, v237
	v_mov_b32_e32 v200, v238
	v_mov_b32_e32 v201, v242
	v_mov_b32_e32 v242, v239
	v_pk_add_f32 v[198:199], v[198:199], v[240:241]
	v_pk_add_f32 v[200:201], v[200:201], v[242:243]
	v_div_fixup_f32 v196, v197, v196, 1.0
	v_pk_add_f32 v[198:199], v[198:199], v[200:201]
	s_nop 0
	v_add_f32_e32 v197, v198, v199
	ds_bpermute_b32 v198, v225, v197
	s_waitcnt lgkmcnt(0)
	v_add_f32_e32 v197, v197, v198
	ds_bpermute_b32 v198, v226, v197
	s_waitcnt lgkmcnt(0)
	v_add_f32_e32 v197, v197, v198
	v_fmamk_f32 v197, v197, 0x3a000000, v213
	v_cmp_gt_f32_e32 vcc, s98, v197
	v_mul_f32_e32 v198, 0x4f800000, v197
	s_nop 0
	v_cndmask_b32_e32 v197, v197, v198, vcc
	v_sqrt_f32_e32 v198, v197
	s_nop 0
	v_add_u32_e32 v199, -1, v198
	v_fma_f32 v200, -v199, v198, v197
	v_cmp_ge_f32_e64 s[46:47], 0, v200
	v_add_u32_e32 v200, 1, v198
	s_nop 0
	v_cndmask_b32_e64 v199, v198, v199, s[46:47]
	v_fma_f32 v198, -v200, v198, v197
	v_cmp_lt_f32_e64 s[46:47], 0, v198
	s_nop 1
	v_cndmask_b32_e64 v198, v199, v200, s[46:47]
	v_mul_f32_e32 v199, 0x37800000, v198
	v_cndmask_b32_e32 v198, v198, v199, vcc
	v_cmp_class_f32_e32 vcc, v197, v214
	s_nop 1
	v_cndmask_b32_e32 v197, v198, v197, vcc
	v_div_scale_f32 v198, s[46:47], v197, v197, 1.0
	v_rcp_f32_e32 v199, v198
	s_nop 0
	v_fma_f32 v200, -v198, v199, 1.0
	v_fmac_f32_e32 v199, v200, v199
	v_div_scale_f32 v200, vcc, 1.0, v197, 1.0
	v_mul_f32_e32 v201, v200, v199
	v_fma_f32 v202, -v198, v201, v200
	v_fmac_f32_e32 v201, v202, v199
	v_fma_f32 v198, -v198, v201, v200
	v_div_fmas_f32 v198, v198, v199, v201
	v_mov_b32_e32 v200, v142
	v_mov_b32_e32 v201, v138
	v_mov_b32_e32 v138, v143
	v_mov_b32_e32 v142, v144
	v_mov_b32_e32 v143, v140
	v_mov_b32_e32 v140, v145
	v_pk_add_f32 v[138:139], v[200:201], v[138:139]
	v_pk_add_f32 v[140:141], v[142:143], v[140:141]
	v_div_fixup_f32 v198, v198, v197, 1.0
	v_pk_add_f32 v[138:139], v[138:139], v[140:141]
	s_nop 0
	v_add_f32_e32 v138, v138, v139
	ds_bpermute_b32 v139, v225, v138
	s_waitcnt lgkmcnt(0)
	v_add_f32_e32 v138, v138, v139
	ds_bpermute_b32 v139, v226, v138
	s_waitcnt lgkmcnt(0)
	v_add_f32_e32 v138, v138, v139
	v_fmamk_f32 v138, v138, 0x3a000000, v213
	v_cmp_gt_f32_e32 vcc, s98, v138
	v_mul_f32_e32 v139, 0x4f800000, v138
	s_nop 0
	v_cndmask_b32_e32 v138, v138, v139, vcc
	v_sqrt_f32_e32 v139, v138
	s_nop 0
	v_add_u32_e32 v140, -1, v139
	v_fma_f32 v141, -v140, v139, v138
	v_cmp_ge_f32_e64 s[46:47], 0, v141
	v_add_u32_e32 v141, 1, v139
	s_nop 0
	v_cndmask_b32_e64 v140, v139, v140, s[46:47]
	v_fma_f32 v139, -v141, v139, v138
	v_cmp_lt_f32_e64 s[46:47], 0, v139
	s_nop 1
	v_cndmask_b32_e64 v139, v140, v141, s[46:47]
	v_mul_f32_e32 v140, 0x37800000, v139
	v_cndmask_b32_e32 v139, v139, v140, vcc
	v_cmp_class_f32_e32 vcc, v138, v214
	s_nop 1
	v_cndmask_b32_e32 v138, v139, v138, vcc
	v_div_scale_f32 v139, s[46:47], v138, v138, 1.0
	v_rcp_f32_e32 v140, v139
	s_nop 0
	v_fma_f32 v141, -v139, v140, 1.0
	v_fmac_f32_e32 v140, v141, v140
	v_div_scale_f32 v141, vcc, 1.0, v138, 1.0
	v_mul_f32_e32 v142, v141, v140
	v_fma_f32 v143, -v139, v142, v141
	v_fmac_f32_e32 v142, v143, v140
	v_fma_f32 v139, -v139, v142, v141
	v_div_fmas_f32 v139, v139, v140, v142
	v_div_fixup_f32 v200, v139, v138, 1.0
	v_mov_b32_e32 v138, v134
	v_mov_b32_e32 v139, v130
	v_mov_b32_e32 v130, v135
	v_mov_b32_e32 v134, v136
	v_mov_b32_e32 v135, v132
	v_mov_b32_e32 v132, v137
	v_pk_add_f32 v[130:131], v[138:139], v[130:131]
	v_pk_add_f32 v[132:133], v[134:135], v[132:133]
	s_nop 0
	v_pk_add_f32 v[130:131], v[130:131], v[132:133]
	s_nop 0
	v_add_f32_e32 v130, v130, v131
	ds_bpermute_b32 v131, v225, v130
	s_waitcnt lgkmcnt(0)
;     __device__ __forceinline__ void operator()(f32x4 (&acc)[2][2][4][2], const Unit& u, int wr, int wc, int fr, int fq) const {
;     ...
;         for (int ai = 0; ai < 2; ++ai) {
;             f32x4 pa[4], pb[4];
; #pragma unroll
;             for (int m = 0; m < 4; ++m) { const float* sp4 = slots + (size_t)(row0 + ai * HALF + m * 16) * 32 + fq * 8;
;                 asm volatile("global_load_dwordx4 %0, %1, off sc0 sc1" : "=v"(pa[m]) : "v"(sp4) : "memory");
;                 asm volatile("global_load_dwordx4 %0, %1, off offset:16 sc0 sc1" : "=v"(pb[m]) : "v"(sp4) : "memory"); }
;             asm volatile("s_waitcnt vmcnt(0)" : "+v"(pa[0]), "+v"(pa[1]), "+v"(pa[2]), "+v"(pa[3]), "+v"(pb[0]), "+v"(pb[1]), "+v"(pb[2]), "+v"(pb[3]) :: "memory");
; #pragma unroll
;             for (int m = 0; m < 4; ++m) {
;                 float t = ((pa[m].x + pa[m].y) + (pa[m].z + pa[m].w)) + ((pb[m].x + pb[m].y) + (pb[m].z + pb[m].w));
;                 t += __shfl_xor(t, 16); t += __shfl_xor(t, 32);
;                 rs[ai][m] = 1.0f / sqrtf(t * (1.0f / D) + NORM_EPS);
	v_add_f32_e32 v130, v130, v131
	ds_bpermute_b32 v131, v226, v130
	s_waitcnt lgkmcnt(0)
	v_add_f32_e32 v130, v130, v131
	v_fmamk_f32 v130, v130, 0x3a000000, v213
	v_cmp_gt_f32_e32 vcc, s98, v130
	v_mul_f32_e32 v131, 0x4f800000, v130
	s_nop 0
	v_cndmask_b32_e32 v130, v130, v131, vcc
	v_sqrt_f32_e32 v131, v130
	s_nop 0
	v_add_u32_e32 v132, -1, v131
	v_fma_f32 v133, -v132, v131, v130
	v_cmp_ge_f32_e64 s[46:47], 0, v133
	v_add_u32_e32 v133, 1, v131
	s_nop 0
	v_cndmask_b32_e64 v132, v131, v132, s[46:47]
	v_fma_f32 v131, -v133, v131, v130
	v_cmp_lt_f32_e64 s[46:47], 0, v131
	s_nop 1
	v_cndmask_b32_e64 v131, v132, v133, s[46:47]
	v_mul_f32_e32 v132, 0x37800000, v131
	v_cndmask_b32_e32 v131, v131, v132, vcc
	v_cmp_class_f32_e32 vcc, v130, v214
	s_nop 1
	v_cndmask_b32_e32 v130, v131, v130, vcc
	v_div_scale_f32 v131, s[46:47], v130, v130, 1.0
	v_rcp_f32_e32 v132, v131
	s_nop 0
	v_fma_f32 v133, -v131, v132, 1.0
	v_fmac_f32_e32 v132, v133, v132
	v_div_scale_f32 v133, vcc, 1.0, v130, 1.0
	v_mul_f32_e32 v134, v133, v132
	v_fma_f32 v135, -v131, v134, v133
	v_fmac_f32_e32 v134, v135, v132
	v_fma_f32 v131, -v131, v134, v133
	v_div_fmas_f32 v131, v131, v132, v134
	v_div_fixup_f32 v202, v131, v130, 1.0
	v_lshl_add_u64 v[130:131], v[166:167], 0, v[204:205]
	global_load_dwordx4 v[228:231], v[130:131], off sc0 sc1
	global_load_dwordx4 v[232:235], v[130:131], off offset:16 sc0 sc1
	v_lshl_add_u64 v[130:131], v[166:167], 0, v[206:207]
	global_load_dwordx4 v[236:239], v[130:131], off sc0 sc1
	global_load_dwordx4 v[240:243], v[130:131], off offset:16 sc0 sc1
	v_lshl_add_u64 v[130:131], v[166:167], 0, v[208:209]
	global_load_dwordx4 v[142:145], v[130:131], off sc0 sc1
	global_load_dwordx4 v[138:141], v[130:131], off offset:16 sc0 sc1
	v_lshl_add_u64 v[134:135], v[166:167], 0, v[210:211]
	global_load_dwordx4 v[130:133], v[134:135], off sc0 sc1
	global_load_dwordx4 v[134:137], v[134:135], off offset:16 sc0 sc1
	s_nop 0
	s_waitcnt vmcnt(0)
	s_nop 0
	v_mov_b32_e32 v204, v228
	v_mov_b32_e32 v205, v232
	v_mov_b32_e32 v232, v229
	v_mov_b32_e32 v206, v230
	v_mov_b32_e32 v207, v234
	v_mov_b32_e32 v234, v231
	v_pk_add_f32 v[204:205], v[204:205], v[232:233]
	v_pk_add_f32 v[206:207], v[206:207], v[234:235]
	v_mov_b32_e32 v208, v238
	v_pk_add_f32 v[204:205], v[204:205], v[206:207]
	v_mov_b32_e32 v206, v236
	v_add_f32_e32 v197, v204, v205
	ds_bpermute_b32 v199, v225, v197
	v_mov_b32_e32 v207, v240
	v_mov_b32_e32 v240, v237
	v_mov_b32_e32 v209, v242
	v_mov_b32_e32 v242, v239
	s_waitcnt lgkmcnt(0)
	v_add_f32_e32 v197, v197, v199
	ds_bpermute_b32 v199, v226, v197
	v_pk_add_f32 v[206:207], v[206:207], v[240:241]
	v_pk_add_f32 v[208:209], v[208:209], v[242:243]
	s_waitcnt lgkmcnt(0)
	v_add_f32_e32 v197, v197, v199
	v_fmamk_f32 v197, v197, 0x3a000000, v213
	v_cmp_gt_f32_e32 vcc, s98, v197
	v_mul_f32_e32 v199, 0x4f800000, v197
	v_pk_add_f32 v[206:207], v[206:207], v[208:209]
	v_cndmask_b32_e32 v197, v197, v199, vcc
	v_sqrt_f32_e32 v199, v197
	v_mov_b32_e32 v208, v142
	v_mov_b32_e32 v209, v138
	v_mov_b32_e32 v138, v143
	v_add_u32_e32 v201, -1, v199
	v_fma_f32 v203, -v201, v199, v197
	v_cmp_ge_f32_e64 s[46:47], 0, v203
	v_add_u32_e32 v203, 1, v199
	v_mov_b32_e32 v142, v144
	v_cndmask_b32_e64 v201, v199, v201, s[46:47]
	v_fma_f32 v199, -v203, v199, v197
	v_cmp_lt_f32_e64 s[46:47], 0, v199
	v_mov_b32_e32 v143, v140
	v_mov_b32_e32 v140, v145
	v_cndmask_b32_e64 v199, v201, v203, s[46:47]
	v_mul_f32_e32 v201, 0x37800000, v199
	v_cndmask_b32_e32 v199, v199, v201, vcc
	v_cmp_class_f32_e32 vcc, v197, v214
	v_pk_add_f32 v[138:139], v[208:209], v[138:139]
	v_pk_add_f32 v[140:141], v[142:143], v[140:141]
	v_cndmask_b32_e32 v197, v199, v197, vcc
	v_div_scale_f32 v199, s[46:47], v197, v197, 1.0
	v_rcp_f32_e32 v201, v199
	v_pk_add_f32 v[138:139], v[138:139], v[140:141]
	v_fma_f32 v203, -v199, v201, 1.0
	v_fmac_f32_e32 v201, v203, v201
	v_div_scale_f32 v203, vcc, 1.0, v197, 1.0
	v_mul_f32_e32 v204, v203, v201
	v_fma_f32 v205, -v199, v204, v203
	v_fmac_f32_e32 v204, v205, v201
	v_fma_f32 v199, -v199, v204, v203
	v_div_fmas_f32 v199, v199, v201, v204
	v_div_fixup_f32 v204, v199, v197, 1.0
	v_add_f32_e32 v197, v206, v207
	ds_bpermute_b32 v199, v225, v197
	v_add_f32_e32 v138, v138, v139
	ds_bpermute_b32 v139, v225, v138
	s_waitcnt lgkmcnt(1)
	v_add_f32_e32 v197, v197, v199
	ds_bpermute_b32 v199, v226, v197
	s_waitcnt lgkmcnt(1)
	v_add_f32_e32 v138, v138, v139
	ds_bpermute_b32 v139, v226, v138
	s_waitcnt lgkmcnt(1)
	v_add_f32_e32 v197, v197, v199
	v_fmamk_f32 v197, v197, 0x3a000000, v213
	v_cmp_gt_f32_e32 vcc, s98, v197
	v_mul_f32_e32 v199, 0x4f800000, v197
	s_waitcnt lgkmcnt(0)
; __device__ __forceinline__ unsigned pk2(float lo, float hi) { f32x2 v = {lo, hi}; bf16x2_t b = __builtin_convertvector(v, bf16x2_t); return __builtin_bit_cast(unsigned, b); }
; __device__ __forceinline__ void swap16(unsigned& a, unsigned& b) { auto r = __builtin_amdgcn_permlane16_swap(a, b, false, false); a = r[0]; b = r[1]; }
;     __device__ __forceinline__ void operator()(f32x4 (&acc)[2][2][4][2], const Unit& u, int wr, int wc, int fr, int fq) const {
;     ...
;                 rs[ai][m] = 1.0f / sqrtf(t * (1.0f / D) + NORM_EPS);
;             }
;             asm volatile("" ::: "memory");
;         }
;         f32x4 gw[2][2];
; #pragma unroll
;         for (int bj = 0; bj < 2; ++bj)
; #pragma unroll
;             for (int n = 0; n < 2; ++n) gw[bj][n] = *(const f32x4*)(gain + col0 + bj * HALF + n * 16);
; #pragma unroll
;         for (int ai = 0; ai < 2; ++ai)
; #pragma unroll
;             for (int m = 0; m < 4; ++m) { const size_t off = (size_t)(row0 + ai * HALF + m * 16) * D + col0; const float r = rs[ai][m];
; #pragma unroll
;                 for (int bj = 0; bj < 2; ++bj) {
;                     const f32x4 y0 = acc[ai][bj][m][0] * r * gw[bj][0], y1 = acc[ai][bj][m][1] * r * gw[bj][1];
;                     if (FINAL) { *(f32x4*)(out + off + bj * HALF) = y0; *(f32x4*)(out + off + bj * HALF + 16) = y1; }
;                     else {
;                         unsigned a0 = pk2(y0.x, y0.y), a1 = pk2(y0.z, y0.w), b0 = pk2(y1.x, y1.y), b1 = pk2(y1.z, y1.w);
;                         swap16(a0, b0); swap16(a1, b1);
;                         *(u32x4*)(hb + off + bj * HALF + ((fq & 1) ? 12 : 0)) = (u32x4){a0, a1, b0, b1};
;                     }
	v_add_f32_e32 v138, v138, v139
	v_cndmask_b32_e32 v197, v197, v199, vcc
	v_sqrt_f32_e32 v199, v197
	v_fmamk_f32 v138, v138, 0x3a000000, v213
	v_mul_f32_e32 v139, 0x4f800000, v138
	v_add_u32_e32 v201, -1, v199
	v_fma_f32 v203, -v201, v199, v197
	v_cmp_ge_f32_e64 s[46:47], 0, v203
	v_add_u32_e32 v203, 1, v199
	s_nop 0
	v_cndmask_b32_e64 v201, v199, v201, s[46:47]
	v_fma_f32 v199, -v203, v199, v197
	v_cmp_lt_f32_e64 s[46:47], 0, v199
	s_nop 1
	v_cndmask_b32_e64 v199, v201, v203, s[46:47]
	v_mul_f32_e32 v201, 0x37800000, v199
	v_cndmask_b32_e32 v199, v199, v201, vcc
	v_cmp_class_f32_e32 vcc, v197, v214
	s_nop 1
	v_cndmask_b32_e32 v197, v199, v197, vcc
	v_div_scale_f32 v199, s[46:47], v197, v197, 1.0
	v_rcp_f32_e32 v201, v199
	v_pk_mul_f32 v[2:3], v[2:3], v[196:197] op_sel_hi:[1,0]
	v_pk_mul_f32 v[4:5], v[4:5], v[196:197] op_sel_hi:[1,0]
	v_pk_mul_f32 v[6:7], v[6:7], v[196:197] op_sel_hi:[1,0]
	v_fma_f32 v203, -v199, v201, 1.0
	v_fmac_f32_e32 v201, v203, v201
	v_div_scale_f32 v203, vcc, 1.0, v197, 1.0
	v_mul_f32_e32 v205, v203, v201
	v_fma_f32 v206, -v199, v205, v203
	v_fmac_f32_e32 v205, v206, v201
	v_fma_f32 v199, -v199, v205, v203
	v_div_fmas_f32 v199, v199, v201, v205
	v_cmp_gt_f32_e32 vcc, s98, v138
	v_pk_mul_f32 v[8:9], v[8:9], v[196:197] op_sel_hi:[1,0]
	v_div_fixup_f32 v206, v199, v197, 1.0
	v_cndmask_b32_e32 v138, v138, v139, vcc
	v_sqrt_f32_e32 v139, v138
	s_nop 0
	v_add_u32_e32 v140, -1, v139
	v_fma_f32 v141, -v140, v139, v138
	v_cmp_ge_f32_e64 s[46:47], 0, v141
	v_add_u32_e32 v141, 1, v139
	s_nop 0
	v_cndmask_b32_e64 v140, v139, v140, s[46:47]
	v_fma_f32 v139, -v141, v139, v138
	v_cmp_lt_f32_e64 s[46:47], 0, v139
	s_nop 1
	v_cndmask_b32_e64 v139, v140, v141, s[46:47]
	v_mul_f32_e32 v140, 0x37800000, v139
	v_cndmask_b32_e32 v139, v139, v140, vcc
	v_cmp_class_f32_e32 vcc, v138, v214
	s_nop 1
	v_cndmask_b32_e32 v138, v139, v138, vcc
	v_div_scale_f32 v139, s[46:47], v138, v138, 1.0
	v_rcp_f32_e32 v140, v139
	s_nop 0
	v_fma_f32 v141, -v139, v140, 1.0
	v_fmac_f32_e32 v140, v141, v140
	v_div_scale_f32 v141, vcc, 1.0, v138, 1.0
	v_mul_f32_e32 v142, v141, v140
	v_fma_f32 v143, -v139, v142, v141
	v_fmac_f32_e32 v142, v143, v140
	v_fma_f32 v139, -v139, v142, v141
	v_div_fmas_f32 v139, v139, v140, v142
	v_div_fixup_f32 v210, v139, v138, 1.0
	v_mov_b32_e32 v138, v130
	v_mov_b32_e32 v139, v134
	v_mov_b32_e32 v134, v131
	v_pk_add_f32 v[130:131], v[138:139], v[134:135]
	v_mov_b32_e32 v134, v132
	v_mov_b32_e32 v135, v136
	v_mov_b32_e32 v136, v133
	v_pk_add_f32 v[132:133], v[134:135], v[136:137]
	s_nop 0
	v_pk_add_f32 v[130:131], v[130:131], v[132:133]
	s_nop 0
	v_add_f32_e32 v130, v130, v131
	ds_bpermute_b32 v131, v225, v130
	s_waitcnt lgkmcnt(0)
	v_add_f32_e32 v130, v130, v131
	ds_bpermute_b32 v131, v226, v130
	s_waitcnt lgkmcnt(0)
	v_add_f32_e32 v130, v130, v131
	v_fmamk_f32 v130, v130, 0x3a000000, v213
	v_cmp_gt_f32_e32 vcc, s98, v130
	v_mul_f32_e32 v131, 0x4f800000, v130
	s_nop 0
	v_cndmask_b32_e32 v130, v130, v131, vcc
	v_sqrt_f32_e32 v131, v130
	s_nop 0
	v_add_u32_e32 v132, -1, v131
	v_fma_f32 v133, -v132, v131, v130
	v_cmp_ge_f32_e64 s[46:47], 0, v133
	v_add_u32_e32 v133, 1, v131
	s_nop 0
	v_cndmask_b32_e64 v132, v131, v132, s[46:47]
	v_fma_f32 v131, -v133, v131, v130
	v_cmp_lt_f32_e64 s[46:47], 0, v131
	s_nop 1
	v_cndmask_b32_e64 v131, v132, v133, s[46:47]
	v_mul_f32_e32 v132, 0x37800000, v131
	v_cndmask_b32_e32 v131, v131, v132, vcc
	v_cmp_class_f32_e32 vcc, v130, v214
	s_nop 1
	v_cndmask_b32_e32 v130, v131, v130, vcc
	v_div_scale_f32 v131, s[46:47], v130, v130, 1.0
	v_rcp_f32_e32 v132, v131
	s_nop 0
	v_fma_f32 v133, -v131, v132, 1.0
	v_fmac_f32_e32 v132, v133, v132
	v_div_scale_f32 v133, vcc, 1.0, v130, 1.0
	v_mul_f32_e32 v134, v133, v132
	v_fma_f32 v135, -v131, v134, v133
	v_fmac_f32_e32 v134, v135, v132
	v_fma_f32 v131, -v131, v134, v133
	v_div_fmas_f32 v131, v131, v132, v134
	v_div_fixup_f32 v208, v131, v130, 1.0
	global_load_dwordx4 v[130:133], v[172:173], off
	global_load_dwordx4 v[134:137], v[172:173], off offset:64
	global_load_dwordx4 v[138:141], v[172:173], off offset:512
	global_load_dwordx4 v[142:145], v[172:173], off offset:576
	s_and_b64 vcc, exec, s[44:45]
	s_waitcnt vmcnt(3)
	v_pk_mul_f32 v[4:5], v[4:5], v[132:133]
	v_pk_mul_f32 v[2:3], v[2:3], v[130:131]
	s_waitcnt vmcnt(2)
	v_pk_mul_f32 v[8:9], v[8:9], v[136:137]
	v_pk_mul_f32 v[6:7], v[6:7], v[134:135]
	v_cvt_pk_bf16_f32 v2, v2, v3
	v_cvt_pk_bf16_f32 v3, v4, v5
	v_cvt_pk_bf16_f32 v4, v6, v7
	v_cvt_pk_bf16_f32 v5, v8, v9
	s_nop 0
	v_permlane16_swap_b32_e32 v2, v4
	v_permlane16_swap_b32_e32 v3, v5
	v_lshl_add_u64 v[6:7], v[174:175], 0, v[182:183]
	global_store_dwordx4 v[6:7], v[2:5], off sc1
	v_pk_mul_f32 v[8:9], v[14:15], v[196:197] op_sel_hi:[1,0]
	s_nop 0
	v_pk_mul_f32 v[2:3], v[10:11], v[196:197] op_sel_hi:[1,0]
	v_pk_mul_f32 v[4:5], v[12:13], v[196:197] op_sel_hi:[1,0]
	v_pk_mul_f32 v[10:11], v[16:17], v[196:197] op_sel_hi:[1,0]
	s_waitcnt vmcnt(2)
	v_pk_mul_f32 v[4:5], v[4:5], v[140:141]
	v_pk_mul_f32 v[2:3], v[2:3], v[138:139]
	s_waitcnt vmcnt(1)
; __device__ __forceinline__ unsigned pk2(float lo, float hi) { f32x2 v = {lo, hi}; bf16x2_t b = __builtin_convertvector(v, bf16x2_t); return __builtin_bit_cast(unsigned, b); }
; __device__ __forceinline__ void swap16(unsigned& a, unsigned& b) { auto r = __builtin_amdgcn_permlane16_swap(a, b, false, false); a = r[0]; b = r[1]; }
;     __device__ __forceinline__ void operator()(f32x4 (&acc)[2][2][4][2], const Unit& u, int wr, int wc, int fr, int fq) const {
;     ...
;         for (int ai = 0; ai < 2; ++ai)
; #pragma unroll
;             for (int m = 0; m < 4; ++m) { const size_t off = (size_t)(row0 + ai * HALF + m * 16) * D + col0; const float r = rs[ai][m];
; #pragma unroll
;                 for (int bj = 0; bj < 2; ++bj) {
;                     const f32x4 y0 = acc[ai][bj][m][0] * r * gw[bj][0], y1 = acc[ai][bj][m][1] * r * gw[bj][1];
;                     if (FINAL) { *(f32x4*)(out + off + bj * HALF) = y0; *(f32x4*)(out + off + bj * HALF + 16) = y1; }
;                     else {
;                         unsigned a0 = pk2(y0.x, y0.y), a1 = pk2(y0.z, y0.w), b0 = pk2(y1.x, y1.y), b1 = pk2(y1.z, y1.w);
;                         swap16(a0, b0); swap16(a1, b1);
;                         *(u32x4*)(hb + off + bj * HALF + ((fq & 1) ? 12 : 0)) = (u32x4){a0, a1, b0, b1};
;                     }
	v_pk_mul_f32 v[10:11], v[10:11], v[144:145]
	v_pk_mul_f32 v[8:9], v[8:9], v[142:143]
	v_cvt_pk_bf16_f32 v2, v2, v3
	v_cvt_pk_bf16_f32 v3, v4, v5
	v_cvt_pk_bf16_f32 v4, v8, v9
	v_cvt_pk_bf16_f32 v5, v10, v11
	s_nop 0
	v_permlane16_swap_b32_e32 v2, v4
	v_permlane16_swap_b32_e32 v3, v5
	global_store_dwordx4 v[6:7], v[2:5], off offset:256 sc1
	v_pk_mul_f32 v[8:9], v[26:27], v[198:199] op_sel_hi:[1,0]
	v_pk_mul_f32 v[10:11], v[28:29], v[198:199] op_sel_hi:[1,0]
	v_pk_mul_f32 v[2:3], v[18:19], v[198:199] op_sel_hi:[1,0]
	v_pk_mul_f32 v[4:5], v[20:21], v[198:199] op_sel_hi:[1,0]
	v_pk_mul_f32 v[2:3], v[2:3], v[130:131]
	v_pk_mul_f32 v[4:5], v[4:5], v[132:133]
	v_pk_mul_f32 v[10:11], v[10:11], v[136:137]
	v_pk_mul_f32 v[8:9], v[8:9], v[134:135]
	v_lshlrev_b64 v[6:7], 12, v[180:181]
	v_cvt_pk_bf16_f32 v2, v2, v3
	v_cvt_pk_bf16_f32 v3, v4, v5
	v_cvt_pk_bf16_f32 v4, v8, v9
	v_cvt_pk_bf16_f32 v5, v10, v11
	s_nop 0
	v_permlane16_swap_b32_e32 v2, v4
	v_permlane16_swap_b32_e32 v3, v5
	v_lshl_add_u64 v[6:7], v[174:175], 0, v[6:7]
	global_store_dwordx4 v[6:7], v[2:5], off sc1
	v_pk_mul_f32 v[8:9], v[30:31], v[198:199] op_sel_hi:[1,0]
	v_pk_mul_f32 v[10:11], v[32:33], v[198:199] op_sel_hi:[1,0]
	v_pk_mul_f32 v[2:3], v[22:23], v[198:199] op_sel_hi:[1,0]
	v_pk_mul_f32 v[4:5], v[24:25], v[198:199] op_sel_hi:[1,0]
	v_pk_mul_f32 v[2:3], v[2:3], v[138:139]
	v_pk_mul_f32 v[4:5], v[4:5], v[140:141]
	v_pk_mul_f32 v[10:11], v[10:11], v[144:145]
	v_pk_mul_f32 v[8:9], v[8:9], v[142:143]
	v_cvt_pk_bf16_f32 v2, v2, v3
	v_cvt_pk_bf16_f32 v3, v4, v5
	v_cvt_pk_bf16_f32 v4, v8, v9
	v_cvt_pk_bf16_f32 v5, v10, v11
	s_nop 0
	v_permlane16_swap_b32_e32 v2, v4
	v_permlane16_swap_b32_e32 v3, v5
	global_store_dwordx4 v[6:7], v[2:5], off offset:256 sc1
	v_pk_mul_f32 v[8:9], v[42:43], v[200:201] op_sel_hi:[1,0]
	v_pk_mul_f32 v[10:11], v[44:45], v[200:201] op_sel_hi:[1,0]
	v_pk_mul_f32 v[2:3], v[34:35], v[200:201] op_sel_hi:[1,0]
	v_pk_mul_f32 v[4:5], v[36:37], v[200:201] op_sel_hi:[1,0]
	v_pk_mul_f32 v[2:3], v[2:3], v[130:131]
	v_pk_mul_f32 v[4:5], v[4:5], v[132:133]
	v_pk_mul_f32 v[10:11], v[10:11], v[136:137]
	v_pk_mul_f32 v[8:9], v[8:9], v[134:135]
	v_lshlrev_b64 v[6:7], 12, v[186:187]
	v_cvt_pk_bf16_f32 v2, v2, v3
	v_cvt_pk_bf16_f32 v3, v4, v5
	v_cvt_pk_bf16_f32 v4, v8, v9
	v_cvt_pk_bf16_f32 v5, v10, v11
	s_nop 0
	v_permlane16_swap_b32_e32 v2, v4
	v_permlane16_swap_b32_e32 v3, v5
	v_lshl_add_u64 v[6:7], v[174:175], 0, v[6:7]
	global_store_dwordx4 v[6:7], v[2:5], off sc1
	v_pk_mul_f32 v[8:9], v[46:47], v[200:201] op_sel_hi:[1,0]
	v_pk_mul_f32 v[10:11], v[48:49], v[200:201] op_sel_hi:[1,0]
	v_pk_mul_f32 v[2:3], v[38:39], v[200:201] op_sel_hi:[1,0]
	v_pk_mul_f32 v[4:5], v[40:41], v[200:201] op_sel_hi:[1,0]
	v_pk_mul_f32 v[2:3], v[2:3], v[138:139]
	v_pk_mul_f32 v[4:5], v[4:5], v[140:141]
	v_pk_mul_f32 v[10:11], v[10:11], v[144:145]
	v_pk_mul_f32 v[8:9], v[8:9], v[142:143]
	v_cvt_pk_bf16_f32 v2, v2, v3
	v_cvt_pk_bf16_f32 v3, v4, v5
	v_cvt_pk_bf16_f32 v4, v8, v9
	v_cvt_pk_bf16_f32 v5, v10, v11
	s_nop 0
	v_permlane16_swap_b32_e32 v2, v4
	v_permlane16_swap_b32_e32 v3, v5
	global_store_dwordx4 v[6:7], v[2:5], off offset:256 sc1
	v_pk_mul_f32 v[8:9], v[58:59], v[202:203] op_sel_hi:[1,0]
	v_pk_mul_f32 v[10:11], v[60:61], v[202:203] op_sel_hi:[1,0]
	v_pk_mul_f32 v[2:3], v[50:51], v[202:203] op_sel_hi:[1,0]
	v_pk_mul_f32 v[4:5], v[52:53], v[202:203] op_sel_hi:[1,0]
	v_pk_mul_f32 v[2:3], v[2:3], v[130:131]
	v_pk_mul_f32 v[4:5], v[4:5], v[132:133]
	v_pk_mul_f32 v[10:11], v[10:11], v[136:137]
	v_pk_mul_f32 v[8:9], v[8:9], v[134:135]
	v_lshlrev_b64 v[6:7], 12, v[184:185]
	v_cvt_pk_bf16_f32 v2, v2, v3
	v_cvt_pk_bf16_f32 v3, v4, v5
	v_cvt_pk_bf16_f32 v4, v8, v9
	v_cvt_pk_bf16_f32 v5, v10, v11
	s_nop 0
	v_permlane16_swap_b32_e32 v2, v4
	v_permlane16_swap_b32_e32 v3, v5
	v_lshl_add_u64 v[6:7], v[174:175], 0, v[6:7]
	global_store_dwordx4 v[6:7], v[2:5], off sc1
	v_pk_mul_f32 v[8:9], v[62:63], v[202:203] op_sel_hi:[1,0]
	v_pk_mul_f32 v[10:11], v[64:65], v[202:203] op_sel_hi:[1,0]
	v_pk_mul_f32 v[2:3], v[54:55], v[202:203] op_sel_hi:[1,0]
	v_pk_mul_f32 v[4:5], v[56:57], v[202:203] op_sel_hi:[1,0]
	v_pk_mul_f32 v[2:3], v[2:3], v[138:139]
	v_pk_mul_f32 v[4:5], v[4:5], v[140:141]
	v_pk_mul_f32 v[10:11], v[10:11], v[144:145]
	v_pk_mul_f32 v[8:9], v[8:9], v[142:143]
	v_cvt_pk_bf16_f32 v2, v2, v3
	v_cvt_pk_bf16_f32 v3, v4, v5
	v_cvt_pk_bf16_f32 v4, v8, v9
	v_cvt_pk_bf16_f32 v5, v10, v11
	s_nop 0
	v_permlane16_swap_b32_e32 v2, v4
	v_permlane16_swap_b32_e32 v3, v5
	global_store_dwordx4 v[6:7], v[2:5], off offset:256 sc1
	v_pk_mul_f32 v[8:9], v[74:75], v[204:205] op_sel_hi:[1,0]
	v_pk_mul_f32 v[10:11], v[76:77], v[204:205] op_sel_hi:[1,0]
	v_pk_mul_f32 v[2:3], v[66:67], v[204:205] op_sel_hi:[1,0]
	v_pk_mul_f32 v[4:5], v[68:69], v[204:205] op_sel_hi:[1,0]
	v_pk_mul_f32 v[2:3], v[130:131], v[2:3]
	v_pk_mul_f32 v[4:5], v[132:133], v[4:5]
	v_pk_mul_f32 v[10:11], v[136:137], v[10:11]
	v_pk_mul_f32 v[8:9], v[134:135], v[8:9]
	v_lshlrev_b64 v[6:7], 12, v[190:191]
	v_cvt_pk_bf16_f32 v2, v2, v3
	v_cvt_pk_bf16_f32 v3, v4, v5
	v_cvt_pk_bf16_f32 v4, v8, v9
	v_cvt_pk_bf16_f32 v5, v10, v11
	s_nop 0
	v_permlane16_swap_b32_e32 v2, v4
; __device__ __forceinline__ unsigned pk2(float lo, float hi) { f32x2 v = {lo, hi}; bf16x2_t b = __builtin_convertvector(v, bf16x2_t); return __builtin_bit_cast(unsigned, b); }
; __device__ __forceinline__ void swap16(unsigned& a, unsigned& b) { auto r = __builtin_amdgcn_permlane16_swap(a, b, false, false); a = r[0]; b = r[1]; }
;     __device__ __forceinline__ void operator()(f32x4 (&acc)[2][2][4][2], const Unit& u, int wr, int wc, int fr, int fq) const {
;     ...
;         for (int ai = 0; ai < 2; ++ai)
; #pragma unroll
;             for (int m = 0; m < 4; ++m) { const size_t off = (size_t)(row0 + ai * HALF + m * 16) * D + col0; const float r = rs[ai][m];
; #pragma unroll
;                 for (int bj = 0; bj < 2; ++bj) {
;                     const f32x4 y0 = acc[ai][bj][m][0] * r * gw[bj][0], y1 = acc[ai][bj][m][1] * r * gw[bj][1];
;                     if (FINAL) { *(f32x4*)(out + off + bj * HALF) = y0; *(f32x4*)(out + off + bj * HALF + 16) = y1; }
;                     else {
;                         unsigned a0 = pk2(y0.x, y0.y), a1 = pk2(y0.z, y0.w), b0 = pk2(y1.x, y1.y), b1 = pk2(y1.z, y1.w);
;                         swap16(a0, b0); swap16(a1, b1);
;                         *(u32x4*)(hb + off + bj * HALF + ((fq & 1) ? 12 : 0)) = (u32x4){a0, a1, b0, b1};
;                     }
	v_permlane16_swap_b32_e32 v3, v5
	v_lshl_add_u64 v[6:7], v[174:175], 0, v[6:7]
	global_store_dwordx4 v[6:7], v[2:5], off sc1
	v_pk_mul_f32 v[8:9], v[78:79], v[204:205] op_sel_hi:[1,0]
	v_pk_mul_f32 v[10:11], v[80:81], v[204:205] op_sel_hi:[1,0]
	v_pk_mul_f32 v[2:3], v[70:71], v[204:205] op_sel_hi:[1,0]
	v_pk_mul_f32 v[4:5], v[72:73], v[204:205] op_sel_hi:[1,0]
	v_pk_mul_f32 v[2:3], v[138:139], v[2:3]
	v_pk_mul_f32 v[4:5], v[140:141], v[4:5]
	v_pk_mul_f32 v[10:11], v[144:145], v[10:11]
	v_pk_mul_f32 v[8:9], v[142:143], v[8:9]
	v_cvt_pk_bf16_f32 v2, v2, v3
	v_cvt_pk_bf16_f32 v3, v4, v5
	v_cvt_pk_bf16_f32 v4, v8, v9
	v_cvt_pk_bf16_f32 v5, v10, v11
	s_nop 0
	v_permlane16_swap_b32_e32 v2, v4
	v_permlane16_swap_b32_e32 v3, v5
	global_store_dwordx4 v[6:7], v[2:5], off offset:256 sc1
	v_pk_mul_f32 v[8:9], v[90:91], v[206:207] op_sel_hi:[1,0]
	v_pk_mul_f32 v[10:11], v[92:93], v[206:207] op_sel_hi:[1,0]
	v_pk_mul_f32 v[2:3], v[82:83], v[206:207] op_sel_hi:[1,0]
	v_pk_mul_f32 v[4:5], v[84:85], v[206:207] op_sel_hi:[1,0]
	v_pk_mul_f32 v[2:3], v[130:131], v[2:3]
	v_pk_mul_f32 v[4:5], v[132:133], v[4:5]
	v_pk_mul_f32 v[10:11], v[136:137], v[10:11]
	v_pk_mul_f32 v[8:9], v[134:135], v[8:9]
	v_lshlrev_b64 v[6:7], 12, v[188:189]
	v_cvt_pk_bf16_f32 v2, v2, v3
	v_cvt_pk_bf16_f32 v3, v4, v5
	v_cvt_pk_bf16_f32 v4, v8, v9
	v_cvt_pk_bf16_f32 v5, v10, v11
	s_nop 0
	v_permlane16_swap_b32_e32 v2, v4
	v_permlane16_swap_b32_e32 v3, v5
	v_lshl_add_u64 v[6:7], v[174:175], 0, v[6:7]
	global_store_dwordx4 v[6:7], v[2:5], off sc1
	v_pk_mul_f32 v[8:9], v[94:95], v[206:207] op_sel_hi:[1,0]
	v_pk_mul_f32 v[10:11], v[96:97], v[206:207] op_sel_hi:[1,0]
	v_pk_mul_f32 v[2:3], v[86:87], v[206:207] op_sel_hi:[1,0]
	v_pk_mul_f32 v[4:5], v[88:89], v[206:207] op_sel_hi:[1,0]
	v_pk_mul_f32 v[2:3], v[138:139], v[2:3]
	v_pk_mul_f32 v[4:5], v[140:141], v[4:5]
	v_pk_mul_f32 v[10:11], v[144:145], v[10:11]
	v_pk_mul_f32 v[8:9], v[142:143], v[8:9]
	v_cvt_pk_bf16_f32 v2, v2, v3
	v_cvt_pk_bf16_f32 v3, v4, v5
	v_cvt_pk_bf16_f32 v4, v8, v9
	v_cvt_pk_bf16_f32 v5, v10, v11
	s_nop 0
	v_permlane16_swap_b32_e32 v2, v4
	v_permlane16_swap_b32_e32 v3, v5
	global_store_dwordx4 v[6:7], v[2:5], off offset:256 sc1
	v_pk_mul_f32 v[8:9], v[106:107], v[210:211] op_sel_hi:[1,0]
	v_pk_mul_f32 v[10:11], v[108:109], v[210:211] op_sel_hi:[1,0]
	v_pk_mul_f32 v[2:3], v[98:99], v[210:211] op_sel_hi:[1,0]
	v_pk_mul_f32 v[4:5], v[100:101], v[210:211] op_sel_hi:[1,0]
	v_pk_mul_f32 v[2:3], v[130:131], v[2:3]
	v_pk_mul_f32 v[4:5], v[132:133], v[4:5]
	v_pk_mul_f32 v[10:11], v[136:137], v[10:11]
	v_pk_mul_f32 v[8:9], v[134:135], v[8:9]
	v_lshlrev_b64 v[6:7], 12, v[194:195]
	v_cvt_pk_bf16_f32 v2, v2, v3
	v_cvt_pk_bf16_f32 v3, v4, v5
	v_cvt_pk_bf16_f32 v4, v8, v9
	v_cvt_pk_bf16_f32 v5, v10, v11
	s_nop 0
	v_permlane16_swap_b32_e32 v2, v4
	v_permlane16_swap_b32_e32 v3, v5
	v_lshl_add_u64 v[6:7], v[174:175], 0, v[6:7]
	global_store_dwordx4 v[6:7], v[2:5], off sc1
	v_pk_mul_f32 v[8:9], v[110:111], v[210:211] op_sel_hi:[1,0]
	v_pk_mul_f32 v[10:11], v[112:113], v[210:211] op_sel_hi:[1,0]
	v_pk_mul_f32 v[2:3], v[102:103], v[210:211] op_sel_hi:[1,0]
	v_pk_mul_f32 v[4:5], v[104:105], v[210:211] op_sel_hi:[1,0]
	v_pk_mul_f32 v[2:3], v[138:139], v[2:3]
	v_pk_mul_f32 v[4:5], v[140:141], v[4:5]
	v_pk_mul_f32 v[10:11], v[144:145], v[10:11]
	v_pk_mul_f32 v[8:9], v[142:143], v[8:9]
	v_cvt_pk_bf16_f32 v2, v2, v3
	v_cvt_pk_bf16_f32 v3, v4, v5
	v_cvt_pk_bf16_f32 v4, v8, v9
	v_cvt_pk_bf16_f32 v5, v10, v11
	s_nop 0
	v_permlane16_swap_b32_e32 v2, v4
	v_permlane16_swap_b32_e32 v3, v5
	global_store_dwordx4 v[6:7], v[2:5], off offset:256 sc1
	v_pk_mul_f32 v[8:9], v[122:123], v[208:209] op_sel_hi:[1,0]
	v_pk_mul_f32 v[10:11], v[124:125], v[208:209] op_sel_hi:[1,0]
	v_pk_mul_f32 v[2:3], v[114:115], v[208:209] op_sel_hi:[1,0]
	v_pk_mul_f32 v[4:5], v[116:117], v[208:209] op_sel_hi:[1,0]
	v_pk_mul_f32 v[2:3], v[130:131], v[2:3]
	v_pk_mul_f32 v[4:5], v[132:133], v[4:5]
	v_pk_mul_f32 v[10:11], v[136:137], v[10:11]
	v_pk_mul_f32 v[8:9], v[134:135], v[8:9]
	v_lshlrev_b64 v[6:7], 12, v[192:193]
	v_cvt_pk_bf16_f32 v2, v2, v3
	v_cvt_pk_bf16_f32 v3, v4, v5
	v_cvt_pk_bf16_f32 v4, v8, v9
	v_cvt_pk_bf16_f32 v5, v10, v11
	s_nop 0
	v_permlane16_swap_b32_e32 v2, v4
	v_permlane16_swap_b32_e32 v3, v5
	v_lshl_add_u64 v[6:7], v[174:175], 0, v[6:7]
	global_store_dwordx4 v[6:7], v[2:5], off sc1
	v_pk_mul_f32 v[8:9], v[126:127], v[208:209] op_sel_hi:[1,0]
	v_pk_mul_f32 v[10:11], v[128:129], v[208:209] op_sel_hi:[1,0]
	v_pk_mul_f32 v[2:3], v[118:119], v[208:209] op_sel_hi:[1,0]
	v_pk_mul_f32 v[4:5], v[120:121], v[208:209] op_sel_hi:[1,0]
	v_pk_mul_f32 v[2:3], v[138:139], v[2:3]
	v_pk_mul_f32 v[4:5], v[140:141], v[4:5]
	v_pk_mul_f32 v[10:11], v[144:145], v[10:11]
	v_pk_mul_f32 v[8:9], v[142:143], v[8:9]
	v_cvt_pk_bf16_f32 v2, v2, v3
	v_cvt_pk_bf16_f32 v3, v4, v5
	v_cvt_pk_bf16_f32 v4, v8, v9
	v_cvt_pk_bf16_f32 v5, v10, v11
	s_nop 0
	v_permlane16_swap_b32_e32 v2, v4
	v_permlane16_swap_b32_e32 v3, v5
	global_store_dwordx4 v[6:7], v[2:5], off offset:256 sc1
	s_cbranch_vccnz .LBB0_288
	s_andn2_b64 vcc, exec, s[50:51]
	s_cbranch_vccnz .LBB0_287
	s_barrier
	s_branch .LBB0_287
